# r2frag
# speedup vs baseline: 1.0341x; 1.0341x over previous
; __global__ void __launch_bounds__(512, 2) fwd_megakernel(Params kp_) {
;     ...
;                         const int pg = tid & 15, rsub = tid >> 4;
;                         float invrev[8];
; #pragma unroll
;                         for (int e = 0; e < 8; ++e) invrev[e] = exp2f(-(float)(pg * 8 + e) * (13.287712379549449f / 128.f)) * 0.15915494309189535f;
;                         for (int item = bid; item < 1024; item += G) {
;                             const int n = item & 63, bh = item >> 6, h = bh & 3, b = bh >> 2;
;                             const float lg = log1pf(-exp2f(-5.f - (float)h));
;                             const int row0 = b * SEQ + n * 128;
; #pragma unroll 2
;                             for (int it = 0; it < 4; ++it) { const int i = rsub + 32 * it, pos = n * 128 + i;
;                                 bf16* base = proj + (size_t)(row0 + i) * RETP + h * 256 + pg * 8;
;                                 const u32x4 qa = *(const u32x4*)base, qb2 = *(const u32x4*)(base + 128), ka = *(const u32x4*)(base + 1024), kb2 = *(const u32x4*)(base + 1024 + 128);
;                                 const float dq = __expf(lg * (float)(i + 1));
.LBB0_444:
	s_or_b64 exec, exec, s[0:1]
	v_readlane_b32 s2, v254, 37
	v_readlane_b32 s3, v254, 38
	s_mov_b64 s[0:1], -1
	s_and_b64 vcc, exec, s[2:3]
	s_waitcnt lgkmcnt(0)
	s_barrier
	s_cbranch_vccz .LBB0_668
	v_readlane_b32 s0, v253, 6
	v_mov_b32_e32 v7, v199
	v_readlane_b32 s1, v253, 7
	s_andn2_b64 vcc, exec, s[0:1]
	v_readfirstlane_b32 s0, v7
	s_cbranch_vccnz .LBB0_474
	v_and_b32_e32 v154, 15, v199
	v_bfe_u32 v155, v199, 4, 4
	v_lshrrev_b32_e32 v156, 1, v154
	v_sub_u32_e32 v156, v156, v155
	v_mul_i32_i24_e32 v150, 0x3080, v156
	v_and_b32_e32 v157, 1, v154
	v_lshl_add_u32 v150, v157, 8, v150
	v_lshl_add_u32 v150, v155, 4, v150
	v_lshlrev_b32_e32 v157, 4, v154
	v_sub_u32_e32 v150, v150, v157
	v_ashrrev_i32_e32 v151, 31, v150
	v_mov_b32_e32 v156, 0x18400
	v_mov_b32_e32 v157, 0
	v_lshl_add_u64 v[152:153], v[150:151], 0, v[156:157]
	v_bfe_u32 v156, v199, 5, 1
	v_lshlrev_b32_e32 v186, 8, v156
	v_lshl_add_u32 v186, v154, 4, v186
	v_bfe_u32 v156, v199, 4, 1
	v_lshl_add_u32 v186, v156, 3, v186
	v_add_u32_e32 v186, 0x800, v186
	v_mov_b32_e32 v187, 0
	v_lshl_add_u64 v[184:185], s[52:53], 0, v[186:187]
	v_mov_b32_e32 v190, 0x3080
	v_mov_b32_e32 v191, 0
	v_mov_b32_e32 v192, 0x6100
	v_mov_b32_e32 v193, 0
	v_and_b32_e32 v2, 15, v7
	v_lshlrev_b32_e32 v0, 3, v2
	v_or_b32_e32 v1, 7, v0
	v_cvt_f32_ubyte0_e32 v1, v1
	s_ashr_i32 s4, s0, 6
	v_mul_f32_e32 v3, 0xbdd49a78, v1
	s_mov_b32 s0, 0xc2fc0000
	v_cmp_gt_f32_e32 vcc, s0, v3
	v_or_b32_e32 v4, 6, v0
	v_cvt_f32_ubyte0_e32 v4, v4
	v_cndmask_b32_e32 v3, 0, v240, vcc
	v_fmac_f32_e32 v3, 0xbdd49a78, v1
	v_not_b32_e32 v8, 63
	v_mul_f32_e32 v5, 0xbdd49a78, v4
	v_exp_f32_e32 v1, v3
	v_cndmask_b32_e32 v3, 0, v8, vcc
	v_cmp_gt_f32_e32 vcc, s0, v5
	v_ashrrev_i32_e32 v72, 4, v7
	v_ldexp_f32 v1, v1, v3
	v_cndmask_b32_e32 v5, 0, v240, vcc
	v_fmac_f32_e32 v5, 0xbdd49a78, v4
	v_exp_f32_e32 v4, v5
	v_mul_f32_e32 v3, 0.15915494, v1
	v_cndmask_b32_e32 v1, 0, v8, vcc
	v_or_b32_e32 v5, 4, v0
	v_ldexp_f32 v1, v4, v1
	v_mul_f32_e32 v22, 0.15915494, v1
	v_or_b32_e32 v1, 5, v0
	v_cvt_f32_ubyte0_e32 v1, v1
	v_mul_f32_e32 v4, 0xbdd49a78, v1
	v_cmp_gt_f32_e32 vcc, s0, v4
	v_cvt_f32_ubyte0_e32 v5, v5
	v_mul_f32_e32 v6, 0xbdd49a78, v5
	v_cndmask_b32_e32 v4, 0, v240, vcc
	v_fmac_f32_e32 v4, 0xbdd49a78, v1
	v_exp_f32_e32 v1, v4
	v_cndmask_b32_e32 v4, 0, v8, vcc
	v_cmp_gt_f32_e32 vcc, s0, v6
	v_lshlrev_b32_e32 v196, 4, v2
	v_ldexp_f32 v1, v1, v4
	v_cndmask_b32_e32 v6, 0, v240, vcc
	v_fmac_f32_e32 v6, 0xbdd49a78, v5
	v_exp_f32_e32 v5, v6
	v_mul_f32_e32 v20, 0.15915494, v1
	v_cndmask_b32_e32 v1, 0, v8, vcc
	s_lshl_b32 s1, s4, 4
	v_ldexp_f32 v1, v5, v1
	v_mul_f32_e32 v18, 0.15915494, v1
	v_or_b32_e32 v1, 3, v0
	v_cvt_f32_ubyte0_e32 v1, v1
	v_mul_f32_e32 v4, 0xbdd49a78, v1
	v_cmp_gt_f32_e32 vcc, s0, v4
	v_or_b32_e32 v5, 2, v0
	v_cvt_f32_ubyte0_e32 v5, v5
	v_cndmask_b32_e32 v4, 0, v240, vcc
	v_fmac_f32_e32 v4, 0xbdd49a78, v1
	v_mul_f32_e32 v6, 0xbdd49a78, v5
	v_exp_f32_e32 v1, v4
	v_cndmask_b32_e32 v4, 0, v8, vcc
	v_cmp_gt_f32_e32 vcc, s0, v6
	v_cvt_f64_f32_e32 v[24:25], v3
	v_ldexp_f32 v1, v1, v4
	v_cndmask_b32_e32 v6, 0, v240, vcc
	v_fmac_f32_e32 v6, 0xbdd49a78, v5
	v_exp_f32_e32 v5, v6
	v_mul_f32_e32 v16, 0.15915494, v1
	v_cndmask_b32_e32 v1, 0, v8, vcc
	v_mul_lo_u32 v3, v72, s71
	v_ldexp_f32 v1, v5, v1
	v_mul_f32_e32 v14, 0.15915494, v1
	v_or_b32_e32 v1, 1, v0
	v_cvt_f32_ubyte0_e32 v1, v1
	v_mul_f32_e32 v4, 0xbdd49a78, v1
	v_cmp_gt_f32_e32 vcc, s0, v4
	v_cvt_f32_ubyte0_e32 v0, v0
	v_mul_f32_e32 v5, 0xbdd49a78, v0
	v_cndmask_b32_e32 v4, 0, v240, vcc
	v_fmac_f32_e32 v4, 0xbdd49a78, v1
	v_exp_f32_e32 v1, v4
	v_cndmask_b32_e32 v4, 0, v8, vcc
	v_cmp_gt_f32_e32 vcc, s0, v5
	s_add_i32 s0, 0, 0x10800
	v_ldexp_f32 v1, v1, v4
	v_cndmask_b32_e32 v5, 0, v240, vcc
	v_fmac_f32_e32 v5, 0xbdd49a78, v0
	v_exp_f32_e32 v0, v5
	v_mul_f32_e32 v12, 0.15915494, v1
	v_cndmask_b32_e32 v1, 0, v8, vcc
	v_bfe_u32 v11, v7, 4, 2
	v_ldexp_f32 v0, v0, v1
	v_mul_f32_e32 v10, 0.15915494, v0
	v_and_b32_e32 v0, 0xff, v7
	v_lshl_add_u32 v6, v0, 1, s0
	v_and_b32_e32 v1, 15, v0
	v_lshrrev_b32_e32 v0, 4, v0
	v_lshlrev_b32_e32 v0, 12, v0
	v_lshl_or_b32 v0, v1, 4, v0
	v_mov_b32_e32 v1, v197
	v_add3_u32 v75, v3, v196, s0
	s_sub_i32 s0, s1, 19
	v_lshl_add_u64 v[8:9], s[92:93], 0, v[0:1]
	v_or_b32_e32 v73, s1, v2
	v_lshlrev_b32_e32 v1, 2, v11
	v_mul_u32_u24_e32 v3, 0x210, v2
	v_add_u32_e32 v2, s0, v2
	v_readlane_b32 s0, v254, 9
	v_mul_lo_u32 v13, v73, s71
	v_lshlrev_b32_e32 v0, 3, v11
	v_lshlrev_b32_e32 v26, 4, v11
	v_sub_u32_e32 v77, v2, v1
	v_or_b32_e32 v78, 19, v1
	v_mov_b32_e32 v1, v197
	v_readlane_b32 s1, v254, 10
	v_lshl_add_u64 v[4:5], s[52:53], 0, v[196:197]
	v_add3_u32 v74, 0, v13, v26
	v_cvt_f64_f32_e32 v[10:11], v10
	v_cvt_f64_f32_e32 v[12:13], v12
	v_cvt_f64_f32_e32 v[14:15], v14
	v_cvt_f64_f32_e32 v[16:17], v16
	v_cvt_f64_f32_e32 v[18:19], v18
	v_cvt_f64_f32_e32 v[20:21], v20
	v_cvt_f64_f32_e32 v[22:23], v22
	v_add3_u32 v76, v3, v26, 0
	v_lshl_add_u64 v[26:27], s[0:1], 0, v[0:1]
	v_readlane_b32 s5, v254, 2
	v_readlane_b32 s6, v254, 0
	s_mov_b32 s0, s46
	s_branch .LBB0_448

; #define R1_PK(v) (u32x4){pk2(v[0], v[1]), pk2(v[2], v[3]), pk2(v[4], v[5]), pk2(v[6], v[7])}
; __global__ void __launch_bounds__(512, 2) fwd_megakernel(Params kp_) {
;     ...
;                             for (int it = 0; it < 4; ++it) { const int i = rsub + 32 * it, pos = n * 128 + i;
;                                 bf16* base = proj + (size_t)(row0 + i) * RETP + h * 256 + pg * 8;
;                                 const u32x4 qa = *(const u32x4*)base, qb2 = *(const u32x4*)(base + 128), ka = *(const u32x4*)(base + 1024), kb2 = *(const u32x4*)(base + 1024 + 128);
;                                 const float dq = __expf(lg * (float)(i + 1));
;                                 float q1[8], q2[8], k1[8], k2[8], o1[8], o2[8], o3[8], o4[8], d1[8], d2[8];
; #pragma unroll
;                                 for (int e = 0; e < 4; ++e) { q1[2 * e] = bflo(qa[e]); q1[2 * e + 1] = bfhi(qa[e]); q2[2 * e] = bflo(qb2[e]); q2[2 * e + 1] = bfhi(qb2[e]);
;                                     k1[2 * e] = bflo(ka[e]); k1[2 * e + 1] = bfhi(ka[e]); k2[2 * e] = bflo(kb2[e]); k2[2 * e + 1] = bfhi(kb2[e]); }
; #pragma unroll
;                                 for (int e = 0; e < 8; ++e) { const double rv = (double)pos * (double)invrev[e]; const float fr = (float)(rv - rint(rv));
;                                     const float sn = __builtin_amdgcn_sinf(fr), cs = __builtin_amdgcn_cosf(fr);
;                                     o1[e] = q1[e] * cs - q2[e] * sn; o2[e] = q1[e] * sn + q2[e] * cs; o3[e] = (k1[e] * cs - k2[e] * sn) * 0.0625f; o4[e] = (k1[e] * sn + k2[e] * cs) * 0.0625f;
;                                     d1[e] = o1[e] * dq; d2[e] = o2[e] * dq; }
;     ...
;                                 *(u32x4*)(qs + i * 264 + pg * 8) = R1_PK(o1); *(u32x4*)(qs + i * 264 + 128 + pg * 8) = R1_PK(o2);
;                                 *(u32x4*)(ks + i * 264 + pg * 8) = R1_PK(o3); *(u32x4*)(ks + i * 264 + 128 + pg * 8) = R1_PK(o4);
;                                 { bf16* wb = (rep_ + 1 < REP_R1) ? (dmy + i * 256 + pg * 8) : base; *(u32x4*)wb = R1_PK(d1); *(u32x4*)(wb + 128) = R1_PK(d2); }
.LBB0_449:
	v_add_u32_e32 v83, s1, v81
	v_mad_i64_i32 v[30:31], s[8:9], v83, s69, v[28:29]
	global_load_dwordx4 v[0:3], v[30:31], off
	global_load_dwordx4 v[58:61], v[30:31], off offset:256
	global_load_dwordx4 v[62:65], v[30:31], off offset:2048
	global_load_dwordx4 v[66:69], v[30:31], off offset:2304
	v_add_u32_e32 v84, s1, v72
	v_add_u32_e32 v32, 1, v84
	v_cvt_f32_i32_e32 v32, v32
	v_add_u32_e32 v85, s1, v80
	v_cvt_f64_i32_e32 v[70:71], v85
	v_mul_f64 v[36:37], v[70:71], v[12:13]
	v_mul_f32_e32 v32, v79, v32
	v_mul_f32_e32 v32, 0x3fb8aa3b, v32
	v_exp_f32_e32 v86, v32
	v_mul_f64 v[32:33], v[70:71], v[10:11]
	v_rndne_f64_e32 v[32:33], v[32:33]
	v_rndne_f64_e32 v[36:37], v[36:37]
	v_fma_f64 v[32:33], v[70:71], v[10:11], -v[32:33]
	v_fma_f64 v[36:37], v[70:71], v[12:13], -v[36:37]
	v_cvt_f32_f64_e32 v33, v[32:33]
	v_cvt_f32_f64_e32 v35, v[36:37]
	v_sin_f32_e32 v32, v33
	v_cos_f32_e32 v34, v33
	v_sin_f32_e32 v33, v35
	v_cos_f32_e32 v35, v35
	v_mul_f64 v[46:47], v[70:71], v[16:17]
	v_rndne_f64_e32 v[46:47], v[46:47]
	v_fma_f64 v[46:47], v[70:71], v[16:17], -v[46:47]
	v_mul_f64 v[54:55], v[70:71], v[20:21]
	v_rndne_f64_e32 v[54:55], v[54:55]
	v_fma_f64 v[54:55], v[70:71], v[20:21], -v[54:55]
	v_cvt_f32_f64_e32 v51, v[54:55]
	v_mul_f64 v[94:95], v[70:71], v[24:25]
	v_rndne_f64_e32 v[94:95], v[94:95]
	s_add_i32 s1, s1, 64
	s_cmpk_eq_i32 s1, 0x80
	s_waitcnt vmcnt(3)
	v_lshlrev_b32_e32 v36, 16, v0
	s_waitcnt vmcnt(2)
	v_lshlrev_b32_e32 v38, 16, v58
	v_and_b32_e32 v39, 0xffff0000, v58
	v_and_b32_e32 v37, 0xffff0000, v0
	v_pk_mul_f32 v[40:41], v[32:33], v[38:39]
	v_pk_mul_f32 v[38:39], v[34:35], v[38:39]
	v_pk_fma_f32 v[88:89], v[34:35], v[36:37], v[40:41] neg_lo:[0,0,1] neg_hi:[0,0,1]
	s_waitcnt vmcnt(0)
	v_lshlrev_b32_e32 v40, 16, v66
	v_and_b32_e32 v41, 0xffff0000, v66
	v_pk_fma_f32 v[42:43], v[32:33], v[36:37], v[38:39]
	v_lshlrev_b32_e32 v36, 16, v62
	v_and_b32_e32 v37, 0xffff0000, v62
	v_pk_mul_f32 v[38:39], v[32:33], v[40:41]
	v_lshlrev_b32_e32 v56, 16, v60
	v_pk_fma_f32 v[38:39], v[34:35], v[36:37], v[38:39] neg_lo:[0,0,1] neg_hi:[0,0,1]
	v_pk_mul_f32 v[34:35], v[34:35], v[40:41]
	v_mul_f64 v[40:41], v[70:71], v[14:15]
	v_rndne_f64_e32 v[40:41], v[40:41]
	v_fma_f64 v[40:41], v[70:71], v[14:15], -v[40:41]
	v_cvt_f32_f64_e32 v0, v[40:41]
	v_sin_f32_e32 v40, v0
	v_cos_f32_e32 v44, v0
	v_cvt_f32_f64_e32 v0, v[46:47]
	v_sin_f32_e32 v41, v0
	v_cos_f32_e32 v45, v0
	v_lshlrev_b32_e32 v46, 16, v59
	v_and_b32_e32 v47, 0xffff0000, v59
	v_lshlrev_b32_e32 v0, 16, v1
	v_and_b32_e32 v1, 0xffff0000, v1
	v_pk_mul_f32 v[48:49], v[40:41], v[46:47]
	v_pk_mul_f32 v[46:47], v[44:45], v[46:47]
	v_pk_fma_f32 v[90:91], v[44:45], v[0:1], v[48:49] neg_lo:[0,0,1] neg_hi:[0,0,1]
	v_pk_fma_f32 v[52:53], v[40:41], v[0:1], v[46:47]
	v_lshlrev_b32_e32 v46, 16, v67
	v_and_b32_e32 v47, 0xffff0000, v67
	v_lshlrev_b32_e32 v0, 16, v63
	v_and_b32_e32 v1, 0xffff0000, v63
	v_pk_mul_f32 v[48:49], v[40:41], v[46:47]
	v_and_b32_e32 v57, 0xffff0000, v60
	v_pk_fma_f32 v[48:49], v[44:45], v[0:1], v[48:49] neg_lo:[0,0,1] neg_hi:[0,0,1]
	v_pk_mul_f32 v[44:45], v[44:45], v[46:47]
	v_lshlrev_b32_e32 v54, 16, v2
	v_pk_fma_f32 v[0:1], v[40:41], v[0:1], v[44:45]
	v_and_b32_e32 v55, 0xffff0000, v2
	v_pk_mul_f32 v[46:47], v[0:1], s[58:59] op_sel_hi:[1,0]
	v_mul_f64 v[0:1], v[70:71], v[18:19]
	v_rndne_f64_e32 v[0:1], v[0:1]
	v_fma_f64 v[0:1], v[70:71], v[18:19], -v[0:1]
	v_cvt_f32_f64_e32 v1, v[0:1]
	v_sin_f32_e32 v0, v1
	v_cos_f32_e32 v50, v1
	v_sin_f32_e32 v1, v51
	v_cos_f32_e32 v51, v51
	v_lshlrev_b32_e32 v60, 16, v61
	v_and_b32_e32 v61, 0xffff0000, v61
	v_pk_mul_f32 v[58:59], v[0:1], v[56:57]
	v_pk_mul_f32 v[56:57], v[50:51], v[56:57]
	v_pk_fma_f32 v[92:93], v[50:51], v[54:55], v[58:59] neg_lo:[0,0,1] neg_hi:[0,0,1]
	v_pk_fma_f32 v[62:63], v[0:1], v[54:55], v[56:57]
	v_lshlrev_b32_e32 v56, 16, v68
	v_and_b32_e32 v57, 0xffff0000, v68
	v_lshlrev_b32_e32 v54, 16, v64
	v_and_b32_e32 v55, 0xffff0000, v64
	v_pk_mul_f32 v[58:59], v[0:1], v[56:57]
	v_pk_fma_f32 v[32:33], v[32:33], v[36:37], v[34:35]
	v_pk_fma_f32 v[58:59], v[50:51], v[54:55], v[58:59] neg_lo:[0,0,1] neg_hi:[0,0,1]
	v_pk_mul_f32 v[50:51], v[50:51], v[56:57]
	v_pk_mul_f32 v[36:37], v[32:33], s[58:59] op_sel_hi:[1,0]
	v_pk_fma_f32 v[0:1], v[0:1], v[54:55], v[50:51]
	v_pk_mul_f32 v[34:35], v[86:87], v[88:89] op_sel_hi:[0,1]
	v_pk_mul_f32 v[56:57], v[0:1], s[58:59] op_sel_hi:[1,0]
	v_mul_f64 v[0:1], v[70:71], v[22:23]
	v_rndne_f64_e32 v[0:1], v[0:1]
	v_fma_f64 v[0:1], v[70:71], v[22:23], -v[0:1]
	v_fma_f64 v[70:71], v[70:71], v[24:25], -v[94:95]
	v_cvt_f32_f64_e32 v1, v[0:1]
	v_cvt_f32_f64_e32 v2, v[70:71]
	v_sin_f32_e32 v0, v1
	v_cos_f32_e32 v66, v1
	v_sin_f32_e32 v1, v2
	v_cos_f32_e32 v67, v2
	v_lshlrev_b32_e32 v2, 16, v3
	v_and_b32_e32 v3, 0xffff0000, v3
	v_pk_mul_f32 v[70:71], v[0:1], v[60:61]
	v_pk_mul_f32 v[60:61], v[66:67], v[60:61]
	v_pk_fma_f32 v[94:95], v[66:67], v[2:3], v[70:71] neg_lo:[0,0,1] neg_hi:[0,0,1]
	v_pk_fma_f32 v[70:71], v[0:1], v[2:3], v[60:61]
	v_lshlrev_b32_e32 v60, 16, v69
	v_and_b32_e32 v61, 0xffff0000, v69
	v_lshlrev_b32_e32 v2, 16, v65
	v_and_b32_e32 v3, 0xffff0000, v65
	v_pk_mul_f32 v[64:65], v[0:1], v[60:61]
	v_pk_mul_f32 v[60:61], v[66:67], v[60:61]
	v_pk_fma_f32 v[64:65], v[66:67], v[2:3], v[64:65] neg_lo:[0,0,1] neg_hi:[0,0,1]
	v_pk_fma_f32 v[0:1], v[0:1], v[2:3], v[60:61]
	v_pk_mul_f32 v[32:33], v[86:87], v[42:43] op_sel_hi:[0,1]
	v_pk_mul_f32 v[44:45], v[86:87], v[90:91] op_sel_hi:[0,1]
	v_pk_mul_f32 v[40:41], v[86:87], v[52:53] op_sel_hi:[0,1]
	v_pk_mul_f32 v[54:55], v[86:87], v[92:93] op_sel_hi:[0,1]
	v_pk_mul_f32 v[50:51], v[86:87], v[62:63] op_sel_hi:[0,1]
	v_pk_mul_f32 v[68:69], v[64:65], s[58:59] op_sel_hi:[1,0]
	v_pk_mul_f32 v[66:67], v[0:1], s[58:59] op_sel_hi:[1,0]
	v_pk_mul_f32 v[64:65], v[86:87], v[94:95] op_sel_hi:[0,1]
	v_pk_mul_f32 v[60:61], v[86:87], v[70:71] op_sel_hi:[0,1]
	v_cvt_pk_bf16_f32 v0, v88, v89
	v_cvt_pk_bf16_f32 v1, v90, v91
	v_cvt_pk_bf16_f32 v2, v92, v93
	v_cvt_pk_bf16_f32 v3, v94, v95
	v_add_u32_e32 v86, 0xfffef800, v82
	v_pk_mul_f32 v[38:39], v[38:39], s[58:59] op_sel_hi:[1,0]
	v_pk_mul_f32 v[48:49], v[48:49], s[58:59] op_sel_hi:[1,0]
	v_pk_mul_f32 v[58:59], v[58:59], s[58:59] op_sel_hi:[1,0]
	ds_write_b128 v86, v[0:3]
	v_cvt_pk_bf16_f32 v0, v42, v43
	v_cvt_pk_bf16_f32 v1, v52, v53
	v_cvt_pk_bf16_f32 v2, v62, v63
	v_cvt_pk_bf16_f32 v3, v70, v71
	v_add_u32_e32 v42, 0xfffef900, v82
	ds_write_b128 v42, v[0:3]
	v_cvt_pk_bf16_f32 v0, v38, v39
	v_cvt_pk_bf16_f32 v1, v48, v49
	v_cvt_pk_bf16_f32 v2, v58, v59
	v_cvt_pk_bf16_f32 v3, v68, v69
	ds_write_b128 v82, v[0:3]
	v_cvt_pk_bf16_f32 v0, v36, v37
	v_cvt_pk_bf16_f32 v1, v46, v47
	v_cvt_pk_bf16_f32 v2, v56, v57
	v_cvt_pk_bf16_f32 v3, v66, v67
	ds_write_b128 v82, v[0:3] offset:256
	v_cvt_pk_bf16_f32 v0, v34, v35
	v_cvt_pk_bf16_f32 v1, v44, v45
	v_cvt_pk_bf16_f32 v2, v54, v55
	v_cvt_pk_bf16_f32 v3, v64, v65
	s_barrier
; #define R1_PK(v) (u32x4){pk2(v[0], v[1]), pk2(v[2], v[3]), pk2(v[4], v[5]), pk2(v[6], v[7])}
; __global__ void __launch_bounds__(512, 2) fwd_megakernel(Params kp_) {
;     ...
;                             for (int it = 0; it < 4; ++it) { const int i = rsub + 32 * it, pos = n * 128 + i;
;                                 bf16* base = proj + (size_t)(row0 + i) * RETP + h * 256 + pg * 8;
;                                 const u32x4 qa = *(const u32x4*)base, qb2 = *(const u32x4*)(base + 128), ka = *(const u32x4*)(base + 1024), kb2 = *(const u32x4*)(base + 1024 + 128);
;                                 const float dq = __expf(lg * (float)(i + 1));
;                                 float q1[8], q2[8], k1[8], k2[8], o1[8], o2[8], o3[8], o4[8], d1[8], d2[8];
; #pragma unroll
;                                 for (int e = 0; e < 4; ++e) { q1[2 * e] = bflo(qa[e]); q1[2 * e + 1] = bfhi(qa[e]); q2[2 * e] = bflo(qb2[e]); q2[2 * e + 1] = bfhi(qb2[e]);
;                                     k1[2 * e] = bflo(ka[e]); k1[2 * e + 1] = bfhi(ka[e]); k2[2 * e] = bflo(kb2[e]); k2[2 * e + 1] = bfhi(kb2[e]); }
; #pragma unroll
;                                 for (int e = 0; e < 8; ++e) { const double rv = (double)pos * (double)invrev[e]; const float fr = (float)(rv - rint(rv));
;                                     const float sn = __builtin_amdgcn_sinf(fr), cs = __builtin_amdgcn_cosf(fr);
;                                     o1[e] = q1[e] * cs - q2[e] * sn; o2[e] = q1[e] * sn + q2[e] * cs; o3[e] = (k1[e] * cs - k2[e] * sn) * 0.0625f; o4[e] = (k1[e] * sn + k2[e] * cs) * 0.0625f;
;                                     d1[e] = o1[e] * dq; d2[e] = o2[e] * dq; }
;     ...
;                                 *(u32x4*)(qs + i * 264 + pg * 8) = R1_PK(o1); *(u32x4*)(qs + i * 264 + 128 + pg * 8) = R1_PK(o2);
;                                 *(u32x4*)(ks + i * 264 + pg * 8) = R1_PK(o3); *(u32x4*)(ks + i * 264 + 128 + pg * 8) = R1_PK(o4);
;                                 { bf16* wb = (rep_ + 1 < REP_R1) ? (dmy + i * 256 + pg * 8) : base; *(u32x4*)wb = R1_PK(d1); *(u32x4*)(wb + 128) = R1_PK(d2); }
	v_lshl_add_u64 v[154:155], v[30:31], 0, v[150:151]
	global_store_dwordx4 v[154:155], v[0:3], off
	s_nop 1
	v_cvt_pk_bf16_f32 v0, v32, v33
	v_cvt_pk_bf16_f32 v1, v40, v41
	v_cvt_pk_bf16_f32 v2, v50, v51
	v_cvt_pk_bf16_f32 v3, v60, v61
	v_lshl_add_u64 v[158:159], v[30:31], 0, v[152:153]
	global_store_dwordx4 v[158:159], v[0:3], off
	v_add_u32_e32 v32, 33, v84
	v_cvt_f32_i32_e32 v32, v32
	v_add_u32_e32 v0, 32, v83
	v_mad_i64_i32 v[30:31], s[8:9], v0, s69, v[28:29]
	global_load_dwordx4 v[0:3], v[30:31], off
	global_load_dwordx4 v[58:61], v[30:31], off offset:256
	global_load_dwordx4 v[62:65], v[30:31], off offset:2048
	global_load_dwordx4 v[66:69], v[30:31], off offset:2304
	v_mul_f32_e32 v32, v79, v32
	v_add_u32_e32 v33, 32, v85
	v_mul_f32_e32 v32, 0x3fb8aa3b, v32
	v_cvt_f64_i32_e32 v[70:71], v33
	v_exp_f32_e32 v84, v32
	v_mul_f64 v[32:33], v[70:71], v[10:11]
	v_mul_f64 v[36:37], v[70:71], v[12:13]
	v_rndne_f64_e32 v[32:33], v[32:33]
	v_rndne_f64_e32 v[36:37], v[36:37]
	v_fma_f64 v[32:33], v[70:71], v[10:11], -v[32:33]
	v_fma_f64 v[36:37], v[70:71], v[12:13], -v[36:37]
	v_cvt_f32_f64_e32 v33, v[32:33]
	v_cvt_f32_f64_e32 v35, v[36:37]
	v_sin_f32_e32 v32, v33
	v_cos_f32_e32 v34, v33
	v_sin_f32_e32 v33, v35
	v_cos_f32_e32 v35, v35
	v_mul_f64 v[46:47], v[70:71], v[16:17]
	v_rndne_f64_e32 v[46:47], v[46:47]
	v_fma_f64 v[46:47], v[70:71], v[16:17], -v[46:47]
	v_mul_f64 v[54:55], v[70:71], v[20:21]
	v_rndne_f64_e32 v[54:55], v[54:55]
	v_fma_f64 v[54:55], v[70:71], v[20:21], -v[54:55]
	v_cvt_f32_f64_e32 v51, v[54:55]
	v_mul_f64 v[92:93], v[70:71], v[24:25]
	v_rndne_f64_e32 v[92:93], v[92:93]
	v_add_u32_e32 v83, 0xffff3a00, v82
	s_waitcnt vmcnt(3)
	v_lshlrev_b32_e32 v36, 16, v0
	s_waitcnt vmcnt(2)
	v_lshlrev_b32_e32 v38, 16, v58
	v_and_b32_e32 v39, 0xffff0000, v58
	v_and_b32_e32 v37, 0xffff0000, v0
	v_pk_mul_f32 v[40:41], v[32:33], v[38:39]
	v_pk_mul_f32 v[38:39], v[34:35], v[38:39]
	v_pk_fma_f32 v[86:87], v[34:35], v[36:37], v[40:41] neg_lo:[0,0,1] neg_hi:[0,0,1]
	s_waitcnt vmcnt(0)
	v_lshlrev_b32_e32 v40, 16, v66
	v_and_b32_e32 v41, 0xffff0000, v66
	v_pk_fma_f32 v[42:43], v[32:33], v[36:37], v[38:39]
	v_lshlrev_b32_e32 v36, 16, v62
	v_and_b32_e32 v37, 0xffff0000, v62
	v_pk_mul_f32 v[38:39], v[32:33], v[40:41]
	v_lshlrev_b32_e32 v56, 16, v60
	v_pk_fma_f32 v[38:39], v[34:35], v[36:37], v[38:39] neg_lo:[0,0,1] neg_hi:[0,0,1]
	v_pk_mul_f32 v[34:35], v[34:35], v[40:41]
	v_mul_f64 v[40:41], v[70:71], v[14:15]
	v_rndne_f64_e32 v[40:41], v[40:41]
	v_fma_f64 v[40:41], v[70:71], v[14:15], -v[40:41]
	v_cvt_f32_f64_e32 v0, v[40:41]
	v_sin_f32_e32 v40, v0
	v_cos_f32_e32 v44, v0
	v_cvt_f32_f64_e32 v0, v[46:47]
	v_sin_f32_e32 v41, v0
	v_cos_f32_e32 v45, v0
	v_lshlrev_b32_e32 v46, 16, v59
	v_and_b32_e32 v47, 0xffff0000, v59
	v_lshlrev_b32_e32 v0, 16, v1
	v_and_b32_e32 v1, 0xffff0000, v1
	v_pk_mul_f32 v[48:49], v[40:41], v[46:47]
	v_pk_mul_f32 v[46:47], v[44:45], v[46:47]
	v_pk_fma_f32 v[88:89], v[44:45], v[0:1], v[48:49] neg_lo:[0,0,1] neg_hi:[0,0,1]
	v_pk_fma_f32 v[52:53], v[40:41], v[0:1], v[46:47]
	v_lshlrev_b32_e32 v46, 16, v67
	v_and_b32_e32 v47, 0xffff0000, v67
	v_lshlrev_b32_e32 v0, 16, v63
	v_and_b32_e32 v1, 0xffff0000, v63
	v_pk_mul_f32 v[48:49], v[40:41], v[46:47]
	v_and_b32_e32 v57, 0xffff0000, v60
	v_pk_fma_f32 v[48:49], v[44:45], v[0:1], v[48:49] neg_lo:[0,0,1] neg_hi:[0,0,1]
	v_pk_mul_f32 v[44:45], v[44:45], v[46:47]
	v_lshlrev_b32_e32 v54, 16, v2
	v_pk_fma_f32 v[0:1], v[40:41], v[0:1], v[44:45]
	v_and_b32_e32 v55, 0xffff0000, v2
	v_pk_mul_f32 v[46:47], v[0:1], s[58:59] op_sel_hi:[1,0]
	v_mul_f64 v[0:1], v[70:71], v[18:19]
	v_rndne_f64_e32 v[0:1], v[0:1]
	v_fma_f64 v[0:1], v[70:71], v[18:19], -v[0:1]
	v_cvt_f32_f64_e32 v1, v[0:1]
	v_sin_f32_e32 v0, v1
	v_cos_f32_e32 v50, v1
	v_sin_f32_e32 v1, v51
	v_cos_f32_e32 v51, v51
	v_lshlrev_b32_e32 v60, 16, v61
	v_and_b32_e32 v61, 0xffff0000, v61
	v_pk_mul_f32 v[58:59], v[0:1], v[56:57]
	v_pk_mul_f32 v[56:57], v[50:51], v[56:57]
	v_pk_fma_f32 v[90:91], v[50:51], v[54:55], v[58:59] neg_lo:[0,0,1] neg_hi:[0,0,1]
	v_pk_fma_f32 v[62:63], v[0:1], v[54:55], v[56:57]
	v_lshlrev_b32_e32 v56, 16, v68
	v_and_b32_e32 v57, 0xffff0000, v68
	v_lshlrev_b32_e32 v54, 16, v64
	v_and_b32_e32 v55, 0xffff0000, v64
	v_pk_mul_f32 v[58:59], v[0:1], v[56:57]
	v_pk_fma_f32 v[32:33], v[32:33], v[36:37], v[34:35]
	v_pk_fma_f32 v[58:59], v[50:51], v[54:55], v[58:59] neg_lo:[0,0,1] neg_hi:[0,0,1]
	v_pk_mul_f32 v[50:51], v[50:51], v[56:57]
	v_pk_mul_f32 v[38:39], v[38:39], s[58:59] op_sel_hi:[1,0]
	v_pk_fma_f32 v[0:1], v[0:1], v[54:55], v[50:51]
	v_pk_mul_f32 v[36:37], v[32:33], s[58:59] op_sel_hi:[1,0]
	v_pk_mul_f32 v[56:57], v[0:1], s[58:59] op_sel_hi:[1,0]
	v_mul_f64 v[0:1], v[70:71], v[22:23]
	v_rndne_f64_e32 v[0:1], v[0:1]
	v_fma_f64 v[0:1], v[70:71], v[22:23], -v[0:1]
	v_fma_f64 v[70:71], v[70:71], v[24:25], -v[92:93]
	v_cvt_f32_f64_e32 v1, v[0:1]
	v_cvt_f32_f64_e32 v2, v[70:71]
	v_sin_f32_e32 v0, v1
	v_cos_f32_e32 v66, v1
	v_sin_f32_e32 v1, v2
	v_cos_f32_e32 v67, v2
	v_lshlrev_b32_e32 v2, 16, v3
	v_and_b32_e32 v3, 0xffff0000, v3
	v_pk_mul_f32 v[70:71], v[0:1], v[60:61]
	v_pk_mul_f32 v[60:61], v[66:67], v[60:61]
	v_pk_fma_f32 v[92:93], v[66:67], v[2:3], v[70:71] neg_lo:[0,0,1] neg_hi:[0,0,1]
	v_pk_fma_f32 v[70:71], v[0:1], v[2:3], v[60:61]
	v_lshlrev_b32_e32 v60, 16, v69
	v_and_b32_e32 v61, 0xffff0000, v69
	v_lshlrev_b32_e32 v2, 16, v65
	v_and_b32_e32 v3, 0xffff0000, v65
	v_pk_mul_f32 v[64:65], v[0:1], v[60:61]
	v_pk_mul_f32 v[60:61], v[66:67], v[60:61]
	v_pk_fma_f32 v[64:65], v[66:67], v[2:3], v[64:65] neg_lo:[0,0,1] neg_hi:[0,0,1]
	v_pk_fma_f32 v[0:1], v[0:1], v[2:3], v[60:61]
	v_cvt_pk_bf16_f32 v2, v90, v91
; #define LBAR() asm volatile("s_waitcnt lgkmcnt(0)\n\ts_barrier" ::: "memory")
; #define R1_PK(v) (u32x4){pk2(v[0], v[1]), pk2(v[2], v[3]), pk2(v[4], v[5]), pk2(v[6], v[7])}
; __global__ void __launch_bounds__(512, 2) fwd_megakernel(Params kp_) {
;     ...
;                                 *(u32x4*)(qs + i * 264 + pg * 8) = R1_PK(o1); *(u32x4*)(qs + i * 264 + 128 + pg * 8) = R1_PK(o2);
;                                 *(u32x4*)(ks + i * 264 + pg * 8) = R1_PK(o3); *(u32x4*)(ks + i * 264 + 128 + pg * 8) = R1_PK(o4);
;                                 { bf16* wb = (rep_ + 1 < REP_R1) ? (dmy + i * 256 + pg * 8) : base; *(u32x4*)wb = R1_PK(d1); *(u32x4*)(wb + 128) = R1_PK(d2); }
;     ...
;                             }
;                             LBAR();
	v_pk_mul_f32 v[66:67], v[0:1], s[58:59] op_sel_hi:[1,0]
	v_cvt_pk_bf16_f32 v0, v86, v87
	v_cvt_pk_bf16_f32 v1, v88, v89
	v_cvt_pk_bf16_f32 v3, v92, v93
	v_pk_mul_f32 v[32:33], v[84:85], v[42:43] op_sel_hi:[0,1]
	v_pk_mul_f32 v[48:49], v[48:49], s[58:59] op_sel_hi:[1,0]
	v_pk_mul_f32 v[58:59], v[58:59], s[58:59] op_sel_hi:[1,0]
	v_pk_mul_f32 v[68:69], v[64:65], s[58:59] op_sel_hi:[1,0]
	ds_write_b128 v83, v[0:3]
	v_cvt_pk_bf16_f32 v0, v42, v43
	v_cvt_pk_bf16_f32 v1, v52, v53
	v_cvt_pk_bf16_f32 v2, v62, v63
	v_cvt_pk_bf16_f32 v3, v70, v71
	v_add_u32_e32 v42, 0xffff3b00, v82
	ds_write_b128 v42, v[0:3]
	v_cvt_pk_bf16_f32 v0, v38, v39
	v_cvt_pk_bf16_f32 v1, v48, v49
	v_cvt_pk_bf16_f32 v2, v58, v59
	v_cvt_pk_bf16_f32 v3, v68, v69
	v_pk_mul_f32 v[34:35], v[84:85], v[86:87] op_sel_hi:[0,1]
	v_pk_mul_f32 v[44:45], v[84:85], v[88:89] op_sel_hi:[0,1]
	v_pk_mul_f32 v[54:55], v[84:85], v[90:91] op_sel_hi:[0,1]
	v_pk_mul_f32 v[64:65], v[84:85], v[92:93] op_sel_hi:[0,1]
	ds_write_b128 v82, v[0:3] offset:16896
	v_cvt_pk_bf16_f32 v0, v36, v37
	v_cvt_pk_bf16_f32 v1, v46, v47
	v_cvt_pk_bf16_f32 v2, v56, v57
	v_cvt_pk_bf16_f32 v3, v66, v67
	v_pk_mul_f32 v[40:41], v[84:85], v[52:53] op_sel_hi:[0,1]
	v_pk_mul_f32 v[50:51], v[84:85], v[62:63] op_sel_hi:[0,1]
	v_pk_mul_f32 v[60:61], v[84:85], v[70:71] op_sel_hi:[0,1]
	ds_write_b128 v82, v[0:3] offset:17152
	v_cvt_pk_bf16_f32 v0, v34, v35
	v_cvt_pk_bf16_f32 v1, v44, v45
	v_cvt_pk_bf16_f32 v2, v54, v55
	v_cvt_pk_bf16_f32 v3, v64, v65
	s_barrier
	v_lshl_add_u64 v[154:155], v[30:31], 0, v[150:151]
	global_store_dwordx4 v[154:155], v[0:3], off
	v_add_u32_e32 v82, 0x8400, v82
	s_nop 0
	v_cvt_pk_bf16_f32 v0, v32, v33
	v_cvt_pk_bf16_f32 v1, v40, v41
	v_cvt_pk_bf16_f32 v2, v50, v51
	v_cvt_pk_bf16_f32 v3, v60, v61
	v_lshl_add_u64 v[158:159], v[30:31], 0, v[152:153]
	global_store_dwordx4 v[158:159], v[0:3], off
	s_cbranch_scc0 .LBB0_449
	s_waitcnt lgkmcnt(0)
	s_barrier
	s_ashr_i32 s1, s0, 31
	s_lshl_b64 s[8:9], s[0:1], 16
	v_lshl_add_u64 v[0:1], v[8:9], 0, s[8:9]
	s_mov_b32 s1, 0
; __device__ __forceinline__ unsigned pk2(float lo, float hi) { const f32x2_t v = {lo, hi}; const bf16x2_t b = __builtin_convertvector(v, bf16x2_t); return __builtin_bit_cast(unsigned, b); }
; #define MFMA16(a, b, c) __builtin_amdgcn_mfma_f32_16x16x32_bf16((a), (b), (c), 0, 0, 0)
; __global__ void __launch_bounds__(512, 2) fwd_megakernel(Params kp_) {
;     ...
;                             for (int tk = 0; tk < 8; ++tk) { const int task = tid + 512 * tk, d = task & 255, i0 = (task >> 8) * 8;
;                                 float e[8];
; #pragma unroll
;                                 for (int q = 0; q < 8; ++q) e[q] = bf2f(ks[(i0 + q) * 264 + d]) * __expf(lg * (float)(127 - i0 - q));
;                                 u32x4 w; w.x = pk2(e[0], e[1]); w.y = pk2(e[2], e[3]); w.z = pk2(e[4], e[5]); w.w = pk2(e[6], e[7]);
;                                 *(u32x4*)(KDT + (size_t)item * 32768 + d * 128 + i0) = w; }
;                             { const int ti = wave;
; #pragma unroll 2
;                               for (int tj = 0; tj < 8; ++tj) {
;                                   f32x4 acc = {0.f, 0.f, 0.f, 0.f};
;                                   if (tj <= ti) {
;                                       const bf16* Qb = qs + (ti * 16 + r16) * 264 + g4 * 8; const bf16* Kb2 = ks + (tj * 16 + r16) * 264 + g4 * 8;
; #pragma unroll
;                                       for (int k0 = 0; k0 < 256; k0 += 32) acc = MFMA16(*(const bf16x8*)(Kb2 + k0), *(const bf16x8*)(Qb + k0), acc);
;                                   }
;                                   const int i = ti * 16 + r16; float v4[4];
; #pragma unroll
;                                   for (int j = 0; j < 4; ++j) { const int jj = tj * 16 + g4 * 4 + j; v4[j] = (i >= jj) ? acc[j] * __expf(lg * (float)(i - jj)) : 0.f; }
;                                   bf16* ap = (rep_ + 1 < REP_R1) ? (dmy + i * 256 + tj * 16 + g4 * 4) : (proj + (size_t)(row0 + i) * RETP + 1024 + h * 256 + tj * 16 + g4 * 4);
;                                   u32x2 w; w.x = pk2(v4[0], v4[1]); w.y = pk2(v4[2], v4[3]); *(u32x2*)ap = w;
.LBB0_451:
	v_add_u32_e32 v40, s1, v7
	v_ashrrev_i32_e32 v3, 5, v40
	v_and_b32_e32 v2, -8, v3
	v_mad_u64_u32 v[28:29], s[8:9], v2, s71, v[6:7]
	v_sub_u32_e32 v29, 0x7f, v2
	v_cvt_f32_i32_e32 v29, v29
	v_or_b32_e32 v3, 7, v3
	v_mad_u64_u32 v[38:39], s[8:9], v3, s71, v[6:7]
	v_mul_f32_e32 v29, v79, v29
	v_mul_f32_e32 v29, 0x3fb8aa3b, v29
	v_exp_f32_e32 v30, v29
	v_or_b32_e32 v29, 1, v2
	v_sub_u32_e32 v29, 0x7f, v29
	v_cvt_f32_i32_e32 v29, v29
	v_sub_u32_e32 v3, 0x7f, v3
	v_cvt_f32_i32_e32 v3, v3
	s_addk_i32 s1, 0x400
	v_mul_f32_e32 v29, v79, v29
	v_mul_f32_e32 v29, 0x3fb8aa3b, v29
	v_exp_f32_e32 v31, v29
	ds_read_u16 v29, v28
	ds_read_u16 v32, v28 offset:528
	v_mul_f32_e32 v3, v79, v3
	v_mul_f32_e32 v3, 0x3fb8aa3b, v3
	s_cmpk_eq_i32 s1, 0x1000
	s_waitcnt lgkmcnt(0)
	v_lshlrev_b32_e32 v33, 16, v32
	v_lshlrev_b32_e32 v32, 16, v29
	v_or_b32_e32 v29, 2, v2
	v_sub_u32_e32 v29, 0x7f, v29
	v_cvt_f32_i32_e32 v29, v29
	v_pk_mul_f32 v[30:31], v[30:31], v[32:33]
	v_mul_f32_e32 v29, v79, v29
	v_mul_f32_e32 v29, 0x3fb8aa3b, v29
	v_exp_f32_e32 v32, v29
	v_or_b32_e32 v29, 3, v2
	v_sub_u32_e32 v29, 0x7f, v29
	v_cvt_f32_i32_e32 v29, v29
	v_mul_f32_e32 v29, v79, v29
	v_mul_f32_e32 v29, 0x3fb8aa3b, v29
	v_exp_f32_e32 v33, v29
	ds_read_u16 v29, v28 offset:1056
	ds_read_u16 v34, v28 offset:1584
	s_waitcnt lgkmcnt(0)
	v_lshlrev_b32_e32 v35, 16, v34
	v_lshlrev_b32_e32 v34, 16, v29
	v_or_b32_e32 v29, 4, v2
	v_sub_u32_e32 v29, 0x7f, v29
	v_cvt_f32_i32_e32 v29, v29
	v_pk_mul_f32 v[32:33], v[32:33], v[34:35]
	v_mul_f32_e32 v29, v79, v29
	v_mul_f32_e32 v29, 0x3fb8aa3b, v29
	v_exp_f32_e32 v34, v29
	v_or_b32_e32 v29, 5, v2
	v_sub_u32_e32 v29, 0x7f, v29
	v_cvt_f32_i32_e32 v29, v29
	v_mul_f32_e32 v29, v79, v29
	v_mul_f32_e32 v29, 0x3fb8aa3b, v29
	v_exp_f32_e32 v35, v29
	ds_read_u16 v29, v28 offset:2112
	ds_read_u16 v36, v28 offset:2640
	s_waitcnt lgkmcnt(0)
	v_lshlrev_b32_e32 v37, 16, v36
	v_lshlrev_b32_e32 v36, 16, v29
	v_or_b32_e32 v29, 6, v2
	v_sub_u32_e32 v29, 0x7f, v29
	v_cvt_f32_i32_e32 v29, v29
	v_pk_mul_f32 v[34:35], v[34:35], v[36:37]
	v_exp_f32_e32 v37, v3
	ds_read_u16 v3, v28 offset:3168
	ds_read_u16 v28, v38
	v_mul_f32_e32 v29, v79, v29
	v_mul_f32_e32 v29, 0x3fb8aa3b, v29
	v_exp_f32_e32 v36, v29
	s_waitcnt lgkmcnt(0)
	v_lshlrev_b32_e32 v29, 16, v28
	v_lshlrev_b32_e32 v28, 16, v3
	v_pk_mul_f32 v[36:37], v[36:37], v[28:29]
	v_ashrrev_i32_e32 v3, 31, v2
	v_cvt_pk_bf16_f32 v28, v30, v31
	v_cvt_pk_bf16_f32 v29, v32, v33
	v_cvt_pk_bf16_f32 v30, v34, v35
	v_cvt_pk_bf16_f32 v31, v36, v37
	v_lshlrev_b32_e32 v2, 4, v2
	v_lshl_add_u64 v[2:3], v[2:3], 1, v[0:1]
	global_store_dwordx4 v[2:3], v[28:31], off
	v_add_u32_e32 v2, 0x200, v40
	v_ashrrev_i32_e32 v3, 5, v2
	v_and_b32_e32 v2, -8, v3
	v_mad_u64_u32 v[28:29], s[8:9], v2, s71, v[6:7]
	v_sub_u32_e32 v29, 0x7f, v2
	v_cvt_f32_i32_e32 v29, v29
	v_or_b32_e32 v3, 7, v3
	v_mad_u64_u32 v[38:39], s[8:9], v3, s71, v[6:7]
	v_mul_f32_e32 v29, v79, v29
	v_mul_f32_e32 v29, 0x3fb8aa3b, v29
	v_exp_f32_e32 v30, v29
	v_or_b32_e32 v29, 1, v2
	v_sub_u32_e32 v29, 0x7f, v29
	v_cvt_f32_i32_e32 v29, v29
	v_sub_u32_e32 v3, 0x7f, v3
	v_cvt_f32_i32_e32 v3, v3
	v_mul_f32_e32 v29, v79, v29
	v_mul_f32_e32 v29, 0x3fb8aa3b, v29
	v_exp_f32_e32 v31, v29
	ds_read_u16 v29, v28
	ds_read_u16 v32, v28 offset:528
	v_mul_f32_e32 v3, v79, v3
	v_mul_f32_e32 v3, 0x3fb8aa3b, v3
	s_waitcnt lgkmcnt(0)
	v_lshlrev_b32_e32 v33, 16, v32
	v_lshlrev_b32_e32 v32, 16, v29
	v_or_b32_e32 v29, 2, v2
	v_sub_u32_e32 v29, 0x7f, v29
	v_cvt_f32_i32_e32 v29, v29
	v_pk_mul_f32 v[30:31], v[30:31], v[32:33]
	v_mul_f32_e32 v29, v79, v29
	v_mul_f32_e32 v29, 0x3fb8aa3b, v29
	v_exp_f32_e32 v32, v29
	v_or_b32_e32 v29, 3, v2
	v_sub_u32_e32 v29, 0x7f, v29
	v_cvt_f32_i32_e32 v29, v29
	v_mul_f32_e32 v29, v79, v29
	v_mul_f32_e32 v29, 0x3fb8aa3b, v29
	v_exp_f32_e32 v33, v29
	ds_read_u16 v29, v28 offset:1056
	ds_read_u16 v34, v28 offset:1584
	s_waitcnt lgkmcnt(0)
	v_lshlrev_b32_e32 v35, 16, v34
	v_lshlrev_b32_e32 v34, 16, v29
	v_or_b32_e32 v29, 4, v2
	v_sub_u32_e32 v29, 0x7f, v29
	v_cvt_f32_i32_e32 v29, v29
	v_pk_mul_f32 v[32:33], v[32:33], v[34:35]
	v_mul_f32_e32 v29, v79, v29
	v_mul_f32_e32 v29, 0x3fb8aa3b, v29
	v_exp_f32_e32 v34, v29
	v_or_b32_e32 v29, 5, v2
	v_sub_u32_e32 v29, 0x7f, v29
	v_cvt_f32_i32_e32 v29, v29
	v_mul_f32_e32 v29, v79, v29
	v_mul_f32_e32 v29, 0x3fb8aa3b, v29
	v_exp_f32_e32 v35, v29
	ds_read_u16 v29, v28 offset:2112
	ds_read_u16 v36, v28 offset:2640
	s_waitcnt lgkmcnt(0)
	v_lshlrev_b32_e32 v37, 16, v36
	v_lshlrev_b32_e32 v36, 16, v29
	v_or_b32_e32 v29, 6, v2
	v_sub_u32_e32 v29, 0x7f, v29
	v_cvt_f32_i32_e32 v29, v29
	v_pk_mul_f32 v[34:35], v[34:35], v[36:37]
	v_exp_f32_e32 v37, v3
	ds_read_u16 v3, v28 offset:3168
	ds_read_u16 v28, v38
	v_mul_f32_e32 v29, v79, v29
	v_mul_f32_e32 v29, 0x3fb8aa3b, v29
	v_exp_f32_e32 v36, v29
	s_waitcnt lgkmcnt(0)
	v_lshlrev_b32_e32 v29, 16, v28
	v_lshlrev_b32_e32 v28, 16, v3
	v_pk_mul_f32 v[36:37], v[36:37], v[28:29]
	v_ashrrev_i32_e32 v3, 31, v2
	v_cvt_pk_bf16_f32 v28, v30, v31
	v_cvt_pk_bf16_f32 v29, v32, v33
	v_cvt_pk_bf16_f32 v30, v34, v35
	v_cvt_pk_bf16_f32 v31, v36, v37
	v_lshlrev_b32_e32 v2, 4, v2
	v_lshl_add_u64 v[2:3], v[2:3], 1, v[0:1]
	global_store_dwordx4 v[2:3], v[28:31], off
	s_cbranch_scc0 .LBB0_451
	s_and_b32 s1, s7, 3
	s_add_i32 s3, s3, s2
	s_lshl_b32 s1, s1, 9
	v_and_b32_e32 v0, 0x70, v73
	v_add_u32_e32 v0, s3, v0
	v_mov_b32_e32 v196, s1
	v_mad_i64_i32 v[0:1], s[2:3], v0, s69, v[196:197]
	v_lshl_add_u64 v[28:29], v[184:185], 0, v[0:1]
	s_mov_b32 s1, 0
	v_mov_b32_e32 v30, v78
	v_mov_b32_e32 v31, v77
	s_mov_b32 s7, 0
	s_branch .LBB0_454
.LBB0_453:
	s_or_b64 exec, exec, s[2:3]
	v_cvt_pk_bf16_f32 v2, v33, v32
	v_cvt_pk_bf16_f32 v3, v1, v0
	s_add_i32 s7, s7, 2
	s_addk_i32 s1, 0x4200
	v_lshl_add_u64 v[188:189], v[28:29], 0, v[190:191]
	global_store_dwordx2 v[188:189], v[2:3], off
	v_subrev_u32_e32 v31, 32, v31
	v_add_u32_e32 v30, 32, v30
	s_cmp_eq_u32 s1, 0x10800
	v_lshl_add_u64 v[28:29], v[28:29], 0, v[192:193]
	s_cbranch_scc1 .LBB0_447

; __device__ __forceinline__ unsigned pk2(float lo, float hi) { const f32x2_t v = {lo, hi}; const bf16x2_t b = __builtin_convertvector(v, bf16x2_t); return __builtin_bit_cast(unsigned, b); }
; #define MFMA16(a, b, c) __builtin_amdgcn_mfma_f32_16x16x32_bf16((a), (b), (c), 0, 0, 0)
; __global__ void __launch_bounds__(512, 2) fwd_megakernel(Params kp_) {
;     ...
;                               for (int tj = 0; tj < 8; ++tj) {
;                                   f32x4 acc = {0.f, 0.f, 0.f, 0.f};
;                                   if (tj <= ti) {
;                                       const bf16* Qb = qs + (ti * 16 + r16) * 264 + g4 * 8; const bf16* Kb2 = ks + (tj * 16 + r16) * 264 + g4 * 8;
; #pragma unroll
;                                       for (int k0 = 0; k0 < 256; k0 += 32) acc = MFMA16(*(const bf16x8*)(Kb2 + k0), *(const bf16x8*)(Qb + k0), acc);
;                                   }
;                                   const int i = ti * 16 + r16; float v4[4];
; #pragma unroll
;                                   for (int j = 0; j < 4; ++j) { const int jj = tj * 16 + g4 * 4 + j; v4[j] = (i >= jj) ? acc[j] * __expf(lg * (float)(i - jj)) : 0.f; }
;                                   bf16* ap = (rep_ + 1 < REP_R1) ? (dmy + i * 256 + tj * 16 + g4 * 4) : (proj + (size_t)(row0 + i) * RETP + 1024 + h * 256 + tj * 16 + g4 * 4);
;                                   u32x2 w; w.x = pk2(v4[0], v4[1]); w.y = pk2(v4[2], v4[3]); *(u32x2*)ap = w;
.LBB0_464:
	s_or_b64 exec, exec, s[2:3]
	v_cvt_pk_bf16_f32 v2, v33, v35
	v_cvt_pk_bf16_f32 v3, v34, v1
	global_store_dwordx2 v[28:29], v[2:3], off
	s_cmp_ge_i32 s7, s4
	v_mov_b32_e32 v1, 0
	v_mov_b32_e32 v2, 0
	v_mov_b32_e32 v3, 0
	s_cbranch_scc1 .LBB0_466
	v_add_u32_e32 v0, 0x12900, v32
	ds_read_b128 v[0:3], v0
	ds_read_b128 v[34:37], v74
	v_add_u32_e32 v33, 0x12940, v32
	s_waitcnt lgkmcnt(0)
	v_mfma_f32_16x16x32_bf16 v[0:3], v[0:3], v[34:37], 0
	ds_read_b128 v[34:37], v33
	ds_read_b128 v[38:41], v74 offset:64
	v_add_u32_e32 v33, 0x12980, v32
	s_waitcnt lgkmcnt(0)
	v_mfma_f32_16x16x32_bf16 v[0:3], v[34:37], v[38:41], v[0:3]
	ds_read_b128 v[34:37], v33
	ds_read_b128 v[38:41], v74 offset:128
	v_add_u32_e32 v33, 0x129c0, v32
	s_waitcnt lgkmcnt(0)
	v_mfma_f32_16x16x32_bf16 v[0:3], v[34:37], v[38:41], v[0:3]
	ds_read_b128 v[34:37], v33
	ds_read_b128 v[38:41], v74 offset:192
	v_add_u32_e32 v33, 0x12a00, v32
	s_waitcnt lgkmcnt(0)
	v_mfma_f32_16x16x32_bf16 v[0:3], v[34:37], v[38:41], v[0:3]
	ds_read_b128 v[34:37], v33
	ds_read_b128 v[38:41], v74 offset:256
	v_add_u32_e32 v33, 0x12a40, v32
	s_waitcnt lgkmcnt(0)
	v_mfma_f32_16x16x32_bf16 v[0:3], v[34:37], v[38:41], v[0:3]
	ds_read_b128 v[34:37], v33
	ds_read_b128 v[38:41], v74 offset:320
	v_add_u32_e32 v33, 0x12a80, v32
	v_add_u32_e32 v32, 0x12ac0, v32
	s_waitcnt lgkmcnt(0)
	v_mfma_f32_16x16x32_bf16 v[0:3], v[34:37], v[38:41], v[0:3]
	ds_read_b128 v[34:37], v33
	ds_read_b128 v[38:41], v74 offset:384
	s_waitcnt lgkmcnt(0)
	v_mfma_f32_16x16x32_bf16 v[0:3], v[34:37], v[38:41], v[0:3]
	ds_read_b128 v[32:35], v32
	ds_read_b128 v[36:39], v74 offset:448
	s_waitcnt lgkmcnt(0)
	v_mfma_f32_16x16x32_bf16 v[0:3], v[32:35], v[36:39], v[0:3]

; #define R2_LOAD_K(nn) do { const bf16* kdt_ = KDT + ((size_t)bh * 64 + (nn)) * 32768; \
;     _Pragma("unroll") for (int q = 0; q < 4; ++q) { kfr[2 * q] = *(const bf16x8*)(kdt_ + ((2 * wave) * 16 + r16) * 128 + q * 32 + g4 * 8); kfr[2 * q + 1] = *(const bf16x8*)(kdt_ + ((2 * wave + 1) * 16 + r16) * 128 + q * 32 + g4 * 8); } } while (0)
; __global__ void __launch_bounds__(512, 2) fwd_megakernel(Params kp_) {
;     ...
;                         PHASE_IDS;
;                         bf16* ST0 = (bf16*)lds; bf16* VT0 = ST0 + 2 * R2_NCT * 16 * 264;
;                         bf16* dmy = (bf16*)(ws + WS_END) + (size_t)bid * 32768; (void)dmy;
;                         for (int item = bid; item < 16 * R2_NBLK; item += G) {
;                             const int xk_ = item >> 3, blk = xk_ % R2_NBLK, bh = (item & 7) * 2 + xk_ / R2_NBLK, h = bh & 3, b = bh >> 2, e0 = blk * (R2_NCT * 16);
;                             const float lg = log1pf(-exp2f(-5.f - (float)h)), gam = __expf(lg * 128.f);
;                             __syncthreads();
;                             for (int i = tid; i < R2_NCT * 16 * 264; i += 512) ST0[i] = 0;
;                             f32x4 Sacc[R2_NCT][2];
; #pragma unroll
;                             for (int a = 0; a < R2_NCT; ++a) { Sacc[a][0] = (f32x4){0.f, 0.f, 0.f, 0.f}; Sacc[a][1] = (f32x4){0.f, 0.f, 0.f, 0.f}; }
;                             __syncthreads();
;                             bf16x8 afr[12], kfr[8]; u32x4 vreg[R2_NCT / 2];
;     ...
;                             R2_LOAD_A((size_t)b * SEQ); R2_LOAD_K(0);
.LBB0_552:
	s_or_b64 exec, exec, s[0:1]
	v_readlane_b32 s2, v253, 8
	s_waitcnt lgkmcnt(0)
	v_mov_b32_e32 v0, v199
	v_readlane_b32 s3, v253, 9
	s_barrier
	s_and_b64 vcc, exec, s[2:3]
	v_readfirstlane_b32 s0, v0
	s_cbranch_vccz .LBB0_560
	v_and_b32_e32 v1, 15, v0
	s_ashr_i32 s1, s0, 6
	v_and_b32_e32 v4, 63, v0
	v_lshlrev_b32_e32 v4, 3, v4
	v_lshl_or_b32 v4, s1, 12, v4
	v_ashrrev_i32_e32 v5, 31, v4
	s_movk_i32 s2, 0x2100
	v_lshl_add_u64 v[108:109], v[4:5], 1, s[92:93]
	v_mov_b32_e32 v5, 0x2100
	v_bfe_u32 v6, v0, 4, 2
	v_cmp_gt_i32_e32 vcc, s2, v0
	s_lshl_b32 s2, s1, 4
	s_andn2_b32 s0, s0, 63
	v_mad_u32_u24 v125, v1, s71, v5
	v_mov_b32_e32 v5, 0x1100
	s_movk_i32 s1, 0x110
	v_lshlrev_b32_e32 v3, 1, v1
	v_or_b32_e32 v100, s2, v1
	v_bfe_u32 v172, v0, 5, 1
	v_or_b32_e32 v172, s2, v172
	v_mov_b32_e32 v173, 0
	v_and_b32_e32 v174, 31, v0
	v_lshlrev_b32_e32 v174, 4, v174
	v_mov_b32_e32 v175, 0
	v_mov_b32_e32 v170, 0x6100
	v_mov_b32_e32 v171, 0
	v_lshl_add_u64 v[182:183], s[52:53], 0, v[174:175]
	v_lshlrev_b32_e32 v2, 3, v0
	s_add_i32 s0, s0, 0
	v_mul_u32_u24_e32 v124, 0x210, v1
	v_mul_u32_u24_e32 v126, 0x110, v1
	v_mad_u32_u24 v127, v1, s1, v5
	v_mul_u32_u24_e32 v1, 0x840, v6
	v_and_b32_e32 v2, 24, v2
	v_add3_u32 v128, s0, v3, v1
	v_readlane_b32 s0, v254, 11
	s_ashr_i32 s3, s2, 31
	v_lshlrev_b32_e32 v102, 3, v6
	v_mov_b32_e32 v103, v197
	v_ashrrev_i32_e32 v104, 2, v0
	v_lshlrev_b32_e32 v196, 4, v6
	v_mul_u32_u24_e32 v4, 0x88, v2
	v_readlane_b32 s1, v254, 12
	v_mov_b32_e32 v101, s3
	v_ashrrev_i32_e32 v105, 31, v104
	v_lshl_add_u64 v[106:107], s[52:53], 0, v[196:197]
	v_add_u32_e32 v129, 0xfffffe00, v0
	v_lshl_add_u32 v130, v0, 1, 0
	v_lshl_add_u64 v[110:111], s[0:1], 0, v[102:103]
	v_lshlrev_b32_e32 v103, 1, v4
	v_lshlrev_b32_e32 v112, 1, v2
	v_readlane_b32 s16, v254, 13
	s_mov_b32 s17, s46

; #define R2_LOAD_K(nn) do { const bf16* kdt_ = KDT + ((size_t)bh * 64 + (nn)) * 32768; \
;     _Pragma("unroll") for (int q = 0; q < 4; ++q) { kfr[2 * q] = *(const bf16x8*)(kdt_ + ((2 * wave) * 16 + r16) * 128 + q * 32 + g4 * 8); kfr[2 * q + 1] = *(const bf16x8*)(kdt_ + ((2 * wave + 1) * 16 + r16) * 128 + q * 32 + g4 * 8); } } while (0)
; __global__ void __launch_bounds__(512, 2) fwd_megakernel(Params kp_) {
;     ...
;                         for (int item = bid; item < 16 * R2_NBLK; item += G) {
;                             const int xk_ = item >> 3, blk = xk_ % R2_NBLK, bh = (item & 7) * 2 + xk_ / R2_NBLK, h = bh & 3, b = bh >> 2, e0 = blk * (R2_NCT * 16);
;                             const float lg = log1pf(-exp2f(-5.f - (float)h)), gam = __expf(lg * 128.f);
;                             __syncthreads();
;                             for (int i = tid; i < R2_NCT * 16 * 264; i += 512) ST0[i] = 0;
;                             f32x4 Sacc[R2_NCT][2];
; #pragma unroll
;                             for (int a = 0; a < R2_NCT; ++a) { Sacc[a][0] = (f32x4){0.f, 0.f, 0.f, 0.f}; Sacc[a][1] = (f32x4){0.f, 0.f, 0.f, 0.f}; }
;                             __syncthreads();
;                             bf16x8 afr[12], kfr[8]; u32x4 vreg[R2_NCT / 2];
;     ...
;                             R2_LOAD_A((size_t)b * SEQ); R2_LOAD_K(0);
.LBB0_557:
	s_or_b64 exec, exec, s[2:3]
	v_add_f32_e32 v2, -1.0, v1
	v_sub_f32_e32 v3, v2, v1
	v_add_f32_e32 v3, 1.0, v3
	v_sub_f32_e64 v2, -v0, v2
	v_add_f32_e32 v4, v2, v3
	v_cvt_f64_f32_e32 v[2:3], v1
	v_frexp_exp_i32_f64_e32 v2, v[2:3]
	v_subbrev_co_u32_e64 v2, s[0:1], 0, v2, s[0:1]
	v_sub_u32_e32 v3, 0, v2
	v_ldexp_f32 v1, v1, v3
	v_ldexp_f32 v3, v4, v3
	v_add_f32_e32 v4, -1.0, v1
	v_add_f32_e32 v7, 1.0, v1
	v_add_f32_e32 v5, 1.0, v4
	v_add_f32_e32 v8, -1.0, v7
	v_sub_f32_e32 v5, v1, v5
	v_sub_f32_e32 v1, v1, v8
	v_add_f32_e32 v1, v3, v1
	v_add_f32_e32 v5, v3, v5
	v_add_f32_e32 v3, v7, v1
	v_rcp_f32_e32 v8, v3
	v_add_f32_e32 v6, v4, v5
	v_sub_f32_e32 v4, v6, v4
	v_sub_f32_e32 v4, v5, v4
	v_sub_f32_e32 v5, v3, v7
	v_sub_f32_e32 v1, v1, v5
	v_mul_f32_e32 v5, v6, v8
	v_mul_f32_e32 v7, v3, v5
	v_fma_f32 v9, v5, v3, -v7
	v_fmac_f32_e32 v9, v5, v1
	v_add_f32_e32 v10, v7, v9
	v_sub_f32_e32 v11, v6, v10
	v_sub_f32_e32 v6, v6, v11
	v_sub_f32_e32 v7, v10, v7
	v_sub_f32_e32 v6, v6, v10
	v_add_f32_e32 v4, v4, v6
	v_sub_f32_e32 v6, v7, v9
	v_add_f32_e32 v4, v6, v4
	v_add_f32_e32 v6, v11, v4
	v_mul_f32_e32 v7, v8, v6
	v_mul_f32_e32 v9, v3, v7
	v_fma_f32 v3, v7, v3, -v9
	v_fmac_f32_e32 v3, v7, v1
	v_sub_f32_e32 v1, v11, v6
	v_add_f32_e32 v1, v4, v1
	v_add_f32_e32 v4, v9, v3
	v_sub_f32_e32 v10, v6, v4
	v_sub_f32_e32 v6, v6, v10
	v_sub_f32_e32 v9, v4, v9
	v_sub_f32_e32 v4, v6, v4
	v_add_f32_e32 v1, v1, v4
	v_sub_f32_e32 v3, v9, v3
	v_cvt_f32_i32_e32 v2, v2
	v_add_f32_e32 v1, v3, v1
	v_add_f32_e32 v3, v5, v7
	v_add_f32_e32 v1, v10, v1
	v_sub_f32_e32 v4, v3, v5
	v_mul_f32_e32 v1, v8, v1
	v_sub_f32_e32 v4, v7, v4
	v_add_f32_e32 v1, v4, v1
	v_mul_f32_e32 v7, 0x3f317218, v2
	s_mov_b32 s0, 0x3f317218
	v_add_f32_e32 v4, v3, v1
	v_fma_f32 v8, v2, s0, -v7
	v_mul_f32_e32 v5, v4, v4
	v_mov_b32_e32 v6, 0x3ecc95a3
	v_fmac_f32_e32 v8, 0xb102e308, v2
	v_sub_f32_e32 v2, v4, v3
	v_fmamk_f32 v6, v5, 0x3e9b6dac, v6
	v_sub_f32_e32 v1, v1, v2
	v_add_f32_e32 v2, v7, v8
	v_fmaak_f32 v6, v5, v6, 0x3f2aaada
	v_sub_f32_e32 v3, v2, v7
	v_ldexp_f32 v7, v4, 1
	v_mul_f32_e32 v4, v4, v5
	v_mul_f32_e32 v4, v4, v6
	v_add_f32_e32 v5, v7, v4
	v_sub_f32_e32 v6, v5, v7
	v_ldexp_f32 v1, v1, 1
	v_sub_f32_e32 v4, v4, v6
	v_add_f32_e32 v1, v1, v4
	v_add_f32_e32 v4, v5, v1
	v_sub_f32_e32 v5, v4, v5
	v_sub_f32_e32 v1, v1, v5
	v_add_f32_e32 v5, v2, v4
	v_sub_f32_e32 v6, v5, v2
	v_sub_f32_e32 v7, v5, v6
	v_sub_f32_e32 v3, v8, v3
	v_sub_f32_e32 v2, v2, v7
	v_sub_f32_e32 v4, v4, v6
	v_add_f32_e32 v2, v4, v2
	v_add_f32_e32 v4, v3, v1
	v_sub_f32_e32 v6, v4, v3
	v_sub_f32_e32 v7, v4, v6
	v_sub_f32_e32 v3, v3, v7
	v_sub_f32_e32 v1, v1, v6
	v_add_f32_e32 v2, v4, v2
	v_add_f32_e32 v1, v1, v3
	v_add_f32_e32 v3, v5, v2
	v_sub_f32_e32 v4, v3, v5
	v_sub_f32_e32 v2, v2, v4
	v_add_f32_e32 v1, v1, v2
	v_add_f32_e32 v1, v3, v1
	v_mov_b32_e32 v2, 0x7fc00000
	v_cndmask_b32_e64 v1, v2, v1, s[4:5]
	v_mov_b32_e32 v2, 0xff800000
	v_cndmask_b32_e64 v1, v2, v1, s[6:7]
	s_lshl_b32 s0, s18, 4
	v_cndmask_b32_e64 v0, v1, -v0, s[8:9]
	s_sub_i32 s1, s19, s0
	s_ashr_i32 s0, s12, 2
	v_mul_f32_e32 v0, 0x43000000, v0
	s_lshl_b32 s2, s1, 5
	s_ashr_i32 s1, s0, 31
	v_mul_f32_e32 v0, 0x3fb8aa3b, v0
	s_lshl_b64 s[6:7], s[0:1], 13
	v_exp_f32_e32 v114, v0
	v_lshl_add_u64 v[0:1], s[6:7], 0, v[172:173]
	s_waitcnt vmcnt(2)
	v_mov_b64_e32 v[44:45], s[52:53]
	v_mad_u64_u32 v[2:3], s[0:1], v0, s69, v[44:45]
	v_mov_b32_e32 v0, v3
	v_lshl_add_u64 v[46:47], s[6:7], 0, v[104:105]
	v_mad_u64_u32 v[0:1], s[0:1], v1, s69, v[0:1]
	v_mad_u64_u32 v[44:45], s[0:1], v46, s69, v[44:45]
	v_mad_i32_i24 v45, v47, s69, v45
	s_lshl_b32 s0, s13, 10
	s_mov_b32 s1, s95
	s_ashr_i32 s3, s2, 31
	v_lshl_add_u64 v[44:45], v[44:45], 0, s[0:1]
	s_lshl_b64 s[4:5], s[2:3], 1
	v_lshl_add_u64 v[44:45], v[44:45], 0, s[4:5]
	v_mov_b32_e32 v113, v197
	v_mov_b32_e32 v3, v0
	s_lshl_b32 s94, s13, 9
	v_lshl_add_u64 v[44:45], v[44:45], 0, v[112:113]
	v_lshl_add_u64 v[0:1], v[2:3], 0, s[94:95]
	v_lshlrev_b32_e32 v196, 1, v102
	v_add_co_u32_e64 v44, s[0:1], s64, v44
	v_lshl_add_u64 v[176:177], v[0:1], 0, v[174:175]
	s_nop 0
	v_addc_co_u32_e64 v45, s[0:1], 0, v45, s[0:1]
	s_ashr_i32 s13, s12, 31
	s_waitcnt lgkmcnt(0)
	s_barrier
	global_load_dwordx4 v[60:63], v[176:177], off
	global_load_dwordx4 v[12:15], v[176:177], off offset:2048
	v_lshl_add_u64 v[176:177], v[176:177], 0, v[170:171]
	global_load_dwordx4 v[40:43], v[176:177], off
	global_load_dwordx4 v[8:11], v[176:177], off offset:2048
	v_lshl_add_u64 v[176:177], v[176:177], 0, v[170:171]
	global_load_dwordx4 v[36:39], v[176:177], off
	global_load_dwordx4 v[4:7], v[176:177], off offset:2048
	v_lshl_add_u64 v[176:177], v[176:177], 0, v[170:171]
	global_load_dwordx4 v[32:35], v[176:177], off
	global_load_dwordx4 v[0:3], v[176:177], off offset:2048
	v_lshl_add_u64 v[176:177], v[176:177], 0, v[170:171]
	global_load_dwordx4 v[28:31], v[176:177], off
	v_lshl_add_u64 v[176:177], v[176:177], 0, v[170:171]
	global_load_dwordx4 v[24:27], v[176:177], off
	v_lshl_add_u64 v[176:177], v[176:177], 0, v[170:171]
	global_load_dwordx4 v[20:23], v[176:177], off
	v_lshl_add_u64 v[176:177], v[176:177], 0, v[170:171]
	global_load_dwordx4 v[16:19], v[176:177], off
	s_lshl_b64 s[0:1], s[12:13], 22
	v_lshl_add_u64 v[116:117], v[108:109], 0, s[0:1]
	v_mov_b64_e32 v[46:47], v[116:117]
	global_load_dwordx4 v[84:87], v[44:45], off
	global_load_dwordx4 v[52:55], v[46:47], off
	v_add_co_u32_e64 v44, s[0:1], s64, v46
	s_waitcnt vmcnt(14)
	v_lshl_add_u64 v[56:57], v[46:47], 0, s[90:91]
	v_addc_co_u32_e64 v45, s[0:1], 0, v47, s[0:1]
	global_load_dwordx4 v[76:79], v[44:45], off
	global_load_dwordx4 v[68:71], v[46:47], off offset:1024
	global_load_dwordx4 v[48:51], v[46:47], off offset:2048
	global_load_dwordx4 v[72:75], v[56:57], off offset:1024
	s_nop 0
	global_load_dwordx4 v[44:47], v[46:47], off offset:3072
	s_nop 0
	global_load_dwordx4 v[64:67], v[56:57], off offset:2048
	s_nop 0
	global_load_dwordx4 v[56:59], v[56:57], off offset:3072
	s_and_b32 s1, s16, 2
	s_add_i32 s1, s1, s18
	s_and_b32 s1, s1, 3
	s_lshl_b32 s1, s1, 10
	s_add_u32 s4, s4, s1
	s_addc_u32 s5, s5, 0
	v_lshl_add_u64 v[80:81], v[100:101], 0, s[6:7]
	v_mov_b64_e32 v[82:83], s[4:5]
	v_mad_u64_u32 v[82:83], s[4:5], v80, s69, v[82:83]
	v_mov_b32_e32 v80, v83
	v_mad_u64_u32 v[80:81], s[4:5], v81, s69, v[80:81]
	v_mov_b32_e32 v83, v80
	v_mov_b32_e32 v80, 0
	s_mov_b32 s0, 0
	v_lshl_add_u64 v[118:119], v[106:107], 0, s[94:95]
	v_lshl_add_u64 v[180:181], v[182:183], 0, s[94:95]
	v_mov_b32_e32 v120, v114
	v_mov_b32_e32 v121, v114
	v_lshl_add_u64 v[122:123], v[110:111], 0, v[82:83]
	s_mov_b32 s8, 0x8000
	s_lshl_b32 s94, s94, 1
	v_mov_b32_e32 v81, v80
	v_mov_b32_e32 v82, v80
	v_mov_b32_e32 v83, v80
	v_mov_b32_e32 v88, v80
	v_mov_b32_e32 v89, v80
	v_mov_b32_e32 v90, v80
	v_mov_b32_e32 v91, v80
	v_mov_b32_e32 v92, v80
	v_mov_b32_e32 v93, v80
	v_mov_b32_e32 v94, v80
	v_mov_b32_e32 v95, v80
	v_mov_b32_e32 v96, v80
	v_mov_b32_e32 v97, v80
	v_mov_b32_e32 v98, v80
	v_mov_b32_e32 v99, v80
; #define LBAR() asm volatile("s_waitcnt lgkmcnt(0)\n\ts_barrier" ::: "memory")
; #define MFMA16(a, b, c) __builtin_amdgcn_mfma_f32_16x16x32_bf16((a), (b), (c), 0, 0, 0)
; #define R2_BLOAD(slot, q) do { _Pragma("unroll") for (int ct = 0; ct < R2_NCT; ++ct) bq[slot][ct] = ((q) < 8) ? *(const bf16x8*)(ST + (ct * 16 + r16) * 264 + (q) * 32 + g4 * 8) : *(const bf16x8*)(VT + (ct * 16 + r16) * 136 + ((q) - 8) * 32 + g4 * 8); } while (0)
; __global__ void __launch_bounds__(512, 2) fwd_megakernel(Params kp_) {
;     ...
;                             for (int n = 0; n < 64; ++n) {
;                                 const size_t row0 = (size_t)b * SEQ + n * 128;
;                                 bf16* ST = ST0 + (n & 1) * (R2_NCT * 16 * 264); bf16* STn = ST0 + ((n + 1) & 1) * (R2_NCT * 16 * 264); bf16* VT = VT0 + (n & 1) * (R2_NCT * 16 * 136);
; #pragma unroll
;                                 for (int it = 0; it < R2_NCT / 2; ++it) { const int idx_ = tid + 512 * it, i = idx_ >> 2, c8 = idx_ & 3; const u32x4 w = vreg[it];
; #pragma unroll
;                                     for (int e = 0; e < 4; ++e) { VT[(c8 * 8 + 2 * e) * 136 + i] = (bf16)(w[e] & 0xffffu); VT[(c8 * 8 + 2 * e + 1) * 136 + i] = (bf16)(w[e] >> 16); } }
;                                 LBAR();
;                                 f32x4 acc[R2_NCT];
; #pragma unroll
;                                 for (int ct = 0; ct < R2_NCT; ++ct) acc[ct] = (f32x4){0.f, 0.f, 0.f, 0.f};
;                                 {
;                                     bf16x8 bq[3][R2_NCT];
;     ...
;                                     R2_BLOAD(0, 0); R2_BLOAD(1, 1);
; #pragma unroll
;                                     for (int q = 0; q < 12; ++q) {
;                                         if (q + 2 < 12) R2_BLOAD((q + 2) % 3, q + 2);
;                                         __builtin_amdgcn_sched_barrier(0);
; #pragma unroll
;                                         for (int ct = 0; ct < R2_NCT; ++ct) acc[ct] = MFMA16(bq[q % 3][ct], afr[q], acc[ct]);
;                                         __builtin_amdgcn_sched_barrier(0);
;                                     }
;     ...
;                                 }
.LBB0_558:
	s_and_b32 s1, s0, 1
	s_mul_i32 s4, s1, 0x2200
	s_add_i32 s11, s4, 0
	s_lshl_b32 s1, s1, 13
	v_lshlrev_b32_e32 v115, 1, v104
	s_add_i32 s1, s11, s1
	v_add3_u32 v131, s11, v115, v103
	v_add3_u32 v115, s11, v103, v115
	s_waitcnt vmcnt(8)
	ds_write_b16 v131, v84 offset:33792
	ds_write_b16_d16_hi v115, v84 offset:34064
	ds_write_b16 v131, v85 offset:34336
	ds_write_b16_d16_hi v115, v85 offset:34608
	ds_write_b16 v131, v86 offset:34880
	ds_write_b16_d16_hi v115, v86 offset:35152
	ds_write_b16 v131, v87 offset:35424
	ds_write_b16_d16_hi v115, v87 offset:35696
	v_add_u32_e32 v115, s1, v196
	s_waitcnt lgkmcnt(0)
	s_barrier
	v_add_u32_e32 v131, v115, v124
	ds_read_b128 v[84:87], v131
	ds_read_b128 v[132:135], v131 offset:8448
	v_add3_u32 v131, s1, v124, v196
	v_add_u32_e32 v115, v115, v125
	ds_read_b128 v[136:139], v131 offset:64
	ds_read_b128 v[140:143], v131 offset:128
	ds_read_b128 v[144:147], v115 offset:64
	ds_read_b128 v[148:151], v115 offset:128
	s_add_i32 s9, s0, 1
	s_and_b32 s10, 1, s9
	s_add_u32 s4, s6, 0x80
	s_addc_u32 s5, s7, 0
	s_cmp_eq_u32 s0, 63
	s_cselect_b32 s0, s6, s4
	s_cselect_b32 s6, 0x1f8000, s8
	s_cselect_b32 s1, s7, s5
	s_cmp_eq_u32 s10, 1
	s_waitcnt lgkmcnt(5)
	v_mfma_f32_16x16x32_bf16 v[84:87], v[84:87], v[60:63], 0
	s_waitcnt lgkmcnt(4)
	v_mfma_f32_16x16x32_bf16 v[60:63], v[132:135], v[60:63], 0
	ds_read_b128 v[132:135], v131 offset:192
	ds_read_b128 v[152:155], v115 offset:192
	s_waitcnt lgkmcnt(5)
	v_mfma_f32_16x16x32_bf16 v[84:87], v[136:139], v[40:43], v[84:87]
	s_waitcnt lgkmcnt(3)
	v_mfma_f32_16x16x32_bf16 v[40:43], v[144:147], v[40:43], v[60:63]
	s_nop 2
	ds_read_b128 v[60:63], v131 offset:256
	ds_read_b128 v[136:139], v115 offset:256
	v_mfma_f32_16x16x32_bf16 v[84:87], v[140:143], v[36:39], v[84:87]
	s_waitcnt lgkmcnt(4)
	v_mfma_f32_16x16x32_bf16 v[36:39], v[148:151], v[36:39], v[40:43]
	s_nop 2
	ds_read_b128 v[40:43], v131 offset:320
	ds_read_b128 v[140:143], v115 offset:320
	s_waitcnt lgkmcnt(5)
	v_mfma_f32_16x16x32_bf16 v[84:87], v[132:135], v[32:35], v[84:87]
	s_waitcnt lgkmcnt(4)
	v_mfma_f32_16x16x32_bf16 v[32:35], v[152:155], v[32:35], v[36:39]
	s_nop 2
	ds_read_b128 v[36:39], v131 offset:384
	ds_read_b128 v[132:135], v115 offset:384
	s_waitcnt lgkmcnt(5)
	v_mfma_f32_16x16x32_bf16 v[60:63], v[60:63], v[28:31], v[84:87]
	s_waitcnt lgkmcnt(4)
	v_mfma_f32_16x16x32_bf16 v[28:31], v[136:139], v[28:31], v[32:35]
	s_nop 2
	ds_read_b128 v[32:35], v131 offset:448
	ds_read_b128 v[84:87], v115 offset:448
	s_waitcnt lgkmcnt(5)
	v_mfma_f32_16x16x32_bf16 v[40:43], v[40:43], v[24:27], v[60:63]
	s_waitcnt lgkmcnt(4)
	v_mfma_f32_16x16x32_bf16 v[24:27], v[140:143], v[24:27], v[28:31]
	v_add3_u32 v115, s11, v126, v196
	v_add_u32_e32 v131, s11, v196
	v_add_u32_e32 v136, v131, v127
	ds_read_b128 v[28:31], v115 offset:33792
	ds_read_b128 v[60:63], v136 offset:33792
	s_waitcnt lgkmcnt(5)
	v_mfma_f32_16x16x32_bf16 v[36:39], v[36:39], v[20:23], v[40:43]
	s_waitcnt lgkmcnt(4)
	v_mfma_f32_16x16x32_bf16 v[20:23], v[132:135], v[20:23], v[24:27]
	s_nop 2
	ds_read_b128 v[24:27], v115 offset:33856
	ds_read_b128 v[40:43], v136 offset:33856
	s_waitcnt lgkmcnt(5)
	v_mfma_f32_16x16x32_bf16 v[32:35], v[32:35], v[16:19], v[36:39]
	s_waitcnt lgkmcnt(4)
	v_mfma_f32_16x16x32_bf16 v[16:19], v[84:87], v[16:19], v[20:23]
	s_nop 2
	ds_read_b128 v[20:23], v115 offset:33920
	ds_read_b128 v[36:39], v136 offset:33920
	s_waitcnt lgkmcnt(5)
	v_mfma_f32_16x16x32_bf16 v[28:31], v[28:31], v[12:15], v[32:35]
	s_waitcnt lgkmcnt(4)
	v_mfma_f32_16x16x32_bf16 v[12:15], v[60:63], v[12:15], v[16:19]
	s_nop 2
	ds_read_b128 v[16:19], v115 offset:33984
	ds_read_b128 v[32:35], v136 offset:33984
	s_waitcnt lgkmcnt(5)
	v_mfma_f32_16x16x32_bf16 v[24:27], v[24:27], v[8:11], v[28:31]
	s_waitcnt lgkmcnt(4)
	v_mfma_f32_16x16x32_bf16 v[8:11], v[40:43], v[8:11], v[12:15]
	s_waitcnt lgkmcnt(3)
	v_mfma_f32_16x16x32_bf16 v[12:15], v[20:23], v[4:7], v[24:27]
	s_waitcnt lgkmcnt(2)
	v_mfma_f32_16x16x32_bf16 v[4:7], v[36:39], v[4:7], v[8:11]
	s_waitcnt lgkmcnt(1)
	v_mfma_f32_16x16x32_bf16 v[132:135], v[16:19], v[0:3], v[12:15]
	s_waitcnt lgkmcnt(0)
; #define MFMA16(a, b, c) __builtin_amdgcn_mfma_f32_16x16x32_bf16((a), (b), (c), 0, 0, 0)
; __global__ void __launch_bounds__(512, 2) fwd_megakernel(Params kp_) {
;     ...
;                                         for (int ct = 0; ct < R2_NCT; ++ct) acc[ct] = MFMA16(bq[q % 3][ct], afr[q], acc[ct]);
;                                         __builtin_amdgcn_sched_barrier(0);
;                                     }
;     ...
;                                 }
;                                 { const size_t rown = (n < 63) ? row0 + 128 : row0; R2_LOAD_A(rown); }
; #pragma unroll
;                                 for (int ct = 0; ct < R2_NCT; ++ct) { bf16* op = (rep_ + 1 < REP_R2) ? (dmy + (wave * 16 + r16) * 64 + ct * 16 + g4 * 4) : (proj + (row0 + wave * 16 + r16) * RETP + 2048 + h * 512 + e0 + ct * 16 + g4 * 4);
;                                     u32x2 w; w.x = pk2(acc[ct][0], acc[ct][1]); w.y = pk2(acc[ct][2], acc[ct][3]); *(u32x2*)op = w; }
; #pragma unroll
;                                 for (int a = 0; a < R2_NCT; ++a) { Sacc[a][0] = Sacc[a][0] * gam; Sacc[a][1] = Sacc[a][1] * gam; }
;                                 {
;                                     bf16x8 vq[2][R2_NCT];
; #pragma unroll
;                                     for (int dt = 0; dt < R2_NCT; ++dt) vq[0][dt] = *(const bf16x8*)(VT + (dt * 16 + r16) * 136 + g4 * 8);
; #pragma unroll
;                                     for (int q = 0; q < 4; ++q) {
;                                         if (q + 1 < 4) {
; #pragma unroll
;                                             for (int dt = 0; dt < R2_NCT; ++dt) vq[(q + 1) & 1][dt] = *(const bf16x8*)(VT + (dt * 16 + r16) * 136 + (q + 1) * 32 + g4 * 8); }
;                                         __builtin_amdgcn_sched_barrier(0);
; #pragma unroll
;                                         for (int dt = 0; dt < R2_NCT; ++dt) { Sacc[dt][0] = MFMA16(vq[q & 1][dt], kfr[2 * q], Sacc[dt][0]); Sacc[dt][1] = MFMA16(vq[q & 1][dt], kfr[2 * q + 1], Sacc[dt][1]); }
;                                         __builtin_amdgcn_sched_barrier(0);
;                                     }
;                                 }
;                                 R2_LOAD_K(n < 63 ? n + 1 : n);
; #pragma unroll
;                                 for (int dt = 0; dt < R2_NCT; ++dt)
; #pragma unroll
;                                     for (int kt = 0; kt < 2; ++kt)
; #pragma unroll
	v_mfma_f32_16x16x32_bf16 v[136:139], v[32:35], v[0:3], v[4:7]
	v_lshl_add_u64 v[0:1], s[0:1], 0, v[172:173]
	v_mad_u64_u32 v[2:3], s[10:11], v0, s69, v[180:181]
	v_mov_b32_e32 v0, v3
	v_mad_u64_u32 v[0:1], s[10:11], v1, s69, v[0:1]
	v_mov_b32_e32 v3, v0
	global_load_dwordx4 v[60:63], v[2:3], off
	global_load_dwordx4 v[12:15], v[2:3], off offset:2048
	v_lshl_add_u64 v[176:177], v[2:3], 0, v[170:171]
	global_load_dwordx4 v[40:43], v[176:177], off
	global_load_dwordx4 v[8:11], v[176:177], off offset:2048
	v_lshl_add_u64 v[176:177], v[176:177], 0, v[170:171]
	global_load_dwordx4 v[36:39], v[176:177], off
	global_load_dwordx4 v[4:7], v[176:177], off offset:2048
	v_lshl_add_u64 v[176:177], v[176:177], 0, v[170:171]
	global_load_dwordx4 v[32:35], v[176:177], off
	global_load_dwordx4 v[0:3], v[176:177], off offset:2048
	v_lshl_add_u64 v[176:177], v[176:177], 0, v[170:171]
	global_load_dwordx4 v[28:31], v[176:177], off
	v_lshl_add_u64 v[176:177], v[176:177], 0, v[170:171]
	global_load_dwordx4 v[24:27], v[176:177], off
	v_lshl_add_u64 v[176:177], v[176:177], 0, v[170:171]
	global_load_dwordx4 v[20:23], v[176:177], off
	v_lshl_add_u64 v[176:177], v[176:177], 0, v[170:171]
	global_load_dwordx4 v[16:19], v[176:177], off
	v_lshl_add_u64 v[84:85], s[0:1], 0, v[104:105]
	v_mov_b64_e32 v[86:87], s[52:53]
	v_mad_u64_u32 v[86:87], s[0:1], v84, s69, v[86:87]
	v_mov_b32_e32 v84, v87
	v_mad_u64_u32 v[84:85], s[0:1], v85, s69, v[84:85]
	v_mov_b32_e32 v87, v84
	v_lshl_add_u64 v[84:85], v[86:87], 0, s[94:95]
	v_lshl_add_u64 v[84:85], s[2:3], 1, v[84:85]
	v_lshl_add_u64 v[84:85], v[84:85], 0, v[112:113]
	v_add_co_u32_e64 v84, s[0:1], s64, v84
	v_cvt_pk_bf16_f32 v132, v132, v133
	s_nop 0
	v_addc_co_u32_e64 v85, s[0:1], 0, v85, s[0:1]
	global_load_dwordx4 v[84:87], v[84:85], off
	v_cvt_pk_bf16_f32 v133, v134, v135
	global_store_dwordx2 v[122:123], v[132:133], off offset:-32
	v_cvt_pk_bf16_f32 v132, v136, v137
	v_cvt_pk_bf16_f32 v133, v138, v139
	v_mov_b32_e32 v115, v114
	global_store_dwordx2 v[122:123], v[132:133], off
	v_pk_mul_f32 v[98:99], v[114:115], v[98:99]
	v_pk_mul_f32 v[94:95], v[114:115], v[94:95]
	v_pk_mul_f32 v[90:91], v[114:115], v[90:91]
	v_pk_mul_f32 v[82:83], v[114:115], v[82:83]
	v_add_u32_e32 v115, v131, v126
	ds_read_b128 v[132:135], v115 offset:33792
	ds_read_b128 v[136:139], v115 offset:38144
	ds_read_b128 v[140:143], v115 offset:33856
	ds_read_b128 v[144:147], v115 offset:38208
	v_pk_mul_f32 v[96:97], v[120:121], v[96:97]
	v_pk_mul_f32 v[92:93], v[120:121], v[92:93]
	v_pk_mul_f32 v[88:89], v[120:121], v[88:89]
	v_pk_mul_f32 v[80:81], v[120:121], v[80:81]
	s_waitcnt vmcnt(22) lgkmcnt(3)
	v_mfma_f32_16x16x32_bf16 v[96:99], v[132:135], v[52:55], v[96:99]
	s_waitcnt vmcnt(16)
	v_mfma_f32_16x16x32_bf16 v[92:95], v[132:135], v[76:79], v[92:95]
	s_waitcnt lgkmcnt(2)
	v_mfma_f32_16x16x32_bf16 v[52:55], v[136:139], v[52:55], v[88:91]
	v_mfma_f32_16x16x32_bf16 v[76:79], v[136:139], v[76:79], v[80:83]
	s_nop 2
	ds_read_b128 v[80:83], v115 offset:33920
	ds_read_b128 v[88:91], v115 offset:38272
	s_waitcnt vmcnt(20) lgkmcnt(3)
	v_mfma_f32_16x16x32_bf16 v[96:99], v[140:143], v[68:71], v[96:99]
	s_waitcnt vmcnt(18)
	v_mfma_f32_16x16x32_bf16 v[92:95], v[140:143], v[72:75], v[92:95]
	s_waitcnt lgkmcnt(2)
	v_mfma_f32_16x16x32_bf16 v[52:55], v[144:147], v[68:71], v[52:55]
	v_mfma_f32_16x16x32_bf16 v[68:71], v[144:147], v[72:75], v[76:79]
	ds_read_b128 v[72:75], v115 offset:33984
	s_nop 1
	ds_read_b128 v[76:79], v115 offset:38336
	s_waitcnt lgkmcnt(3)
	v_mfma_f32_16x16x32_bf16 v[96:99], v[80:83], v[48:51], v[96:99]
	s_waitcnt vmcnt(16)
	v_mfma_f32_16x16x32_bf16 v[80:83], v[80:83], v[64:67], v[92:95]
	s_waitcnt lgkmcnt(2)
	v_mfma_f32_16x16x32_bf16 v[48:51], v[88:91], v[48:51], v[52:55]
	v_mfma_f32_16x16x32_bf16 v[52:55], v[88:91], v[64:67], v[68:71]
	s_waitcnt lgkmcnt(1)
	v_mfma_f32_16x16x32_bf16 v[96:99], v[72:75], v[44:47], v[96:99]
	s_waitcnt vmcnt(15)
	v_mfma_f32_16x16x32_bf16 v[92:95], v[72:75], v[56:59], v[80:83]
	s_waitcnt lgkmcnt(0)
	v_mfma_f32_16x16x32_bf16 v[88:91], v[76:79], v[44:47], v[48:51]
	v_mfma_f32_16x16x32_bf16 v[80:83], v[76:79], v[56:59], v[52:55]
	s_mov_b32 s7, s95
	v_lshl_add_u64 v[44:45], s[6:7], 1, v[116:117]
	s_nop 0
	v_add_co_u32_e64 v58, s[0:1], s64, v44
	v_lshl_add_u64 v[56:57], v[44:45], 0, s[90:91]
	s_nop 0
	v_addc_co_u32_e64 v59, s[0:1], 0, v45, s[0:1]
	global_load_dwordx4 v[52:55], v[44:45], off
	global_load_dwordx4 v[68:71], v[44:45], off offset:1024
	global_load_dwordx4 v[72:75], v[56:57], off offset:1024
	global_load_dwordx4 v[64:67], v[56:57], off offset:2048
	global_load_dwordx4 v[48:51], v[44:45], off offset:2048
	s_nop 0
	global_load_dwordx4 v[44:47], v[44:45], off offset:3072
	s_nop 0
	global_load_dwordx4 v[76:79], v[58:59], off
	s_nop 0
	global_load_dwordx4 v[56:59], v[56:57], off offset:3072
	s_cselect_b32 s0, 0x4200, 0
	v_cvt_pk_bf16_f32 v115, v96, s0
	v_add_u32_e32 v131, s0, v128
	ds_write_b16 v131, v115
	v_cvt_pk_bf16_f32 v115, v97, s0
	ds_write_b16 v131, v115 offset:528
	v_cvt_pk_bf16_f32 v115, v98, s0
	ds_write_b16 v131, v115 offset:1056
	v_cvt_pk_bf16_f32 v115, v99, s0
	ds_write_b16 v131, v115 offset:1584
	v_cvt_pk_bf16_f32 v115, v92, s0
	ds_write_b16 v131, v115 offset:32
	v_cvt_pk_bf16_f32 v115, v93, s0
	ds_write_b16 v131, v115 offset:560
	v_cvt_pk_bf16_f32 v115, v94, s0
	ds_write_b16 v131, v115 offset:1088
	v_cvt_pk_bf16_f32 v115, v95, s0
	ds_write_b16 v131, v115 offset:1616
	v_cvt_pk_bf16_f32 v115, v88, s0
	ds_write_b16 v131, v115 offset:8448
	v_cvt_pk_bf16_f32 v115, v89, s0
	ds_write_b16 v131, v115 offset:8976
	v_cvt_pk_bf16_f32 v115, v90, s0
	ds_write_b16 v131, v115 offset:9504
	v_cvt_pk_bf16_f32 v115, v91, s0
	ds_write_b16 v131, v115 offset:10032
	v_cvt_pk_bf16_f32 v115, v80, s0
	ds_write_b16 v131, v115 offset:8480
	v_cvt_pk_bf16_f32 v115, v81, s0
	ds_write_b16 v131, v115 offset:9008
	v_cvt_pk_bf16_f32 v115, v82, s0
	ds_write_b16 v131, v115 offset:9536
	v_cvt_pk_bf16_f32 v115, v83, s0
	s_add_i32 s8, s8, 0x8000
	s_mov_b64 s[0:1], 0x184000
	v_lshl_add_u64 v[122:123], v[122:123], 0, s[0:1]
	s_cmp_eq_u32 s9, 64
	s_mov_b64 s[6:7], s[4:5]
	s_mov_b32 s0, s9
	ds_write_b16 v131, v115 offset:10064
	s_cbranch_scc0 .LBB0_558
	v_readlane_b32 s0, v254, 14
	s_add_i32 s17, s17, s88
	s_add_i32 s16, s16, s0
	s_cmpk_gt_i32 s17, 0xff
	s_cbranch_scc0 .LBB0_554
